# scan recurrence: the two rows of a lane packed in one register pair per k (28 VALU per step instead of 32)
# speedup vs baseline: 1.0218x; 1.0033x over previous
.LBB0_144:
	s_or_saveexec_b64 s[12:13], s[42:43]
	s_mul_i32 s45, s45, 0xc000
	v_cndmask_b32_e64 v8, 0, 1, s[40:41]
	s_add_i32 s42, s45, 0
	v_mul_lo_u32 v73, v8, s47
	v_add_u32_e32 v69, s42, v92
	v_lshl_add_u32 v100, v59, 2, s42
	s_xor_b64 exec, exec, s[12:13]
	s_cbranch_execz .LBB0_148
	v_bfe_u32 v119, v171, 4, 2
	v_lshl_add_u32 v118, v119, 2, v100
	v_lshl_add_u32 v119, v119, 6, v94
	v_add_u32_e32 v119, 0x18000, v119
	ds_read_b128 v[12:15], v69 offset:256
	ds_read_b128 v[20:23], v69 offset:768
	ds_read_b64 v[28:29], v118 offset:1280
	ds_read_b128 v[8:11], v69 offset:0
	ds_read_b128 v[16:19], v69 offset:512
	ds_read_b128 v[24:27], v69 offset:1024
	s_setprio 3
	s_waitcnt lgkmcnt(0)
	v_pk_mul_f32 v[110:111], v[0:1], v[12:13] op_sel_hi:[1,0]
	v_pk_mul_f32 v[38:39], v[28:29], v[20:21] op_sel_hi:[1,0]
	v_pk_fma_f32 v[110:111], v[2:3], v[12:13], v[110:111] op_sel:[0,1,0]
	v_pk_mul_f32 v[82:83], v[28:29], v[20:21] op_sel:[0,1]
	v_pk_fma_f32 v[110:111], v[4:5], v[14:15], v[110:111] op_sel_hi:[1,0,1]
	v_pk_mul_f32 v[116:117], v[28:29], v[22:23] op_sel_hi:[1,0]
	v_pk_fma_f32 v[110:111], v[6:7], v[14:15], v[110:111] op_sel:[0,1,0]
	v_pk_mul_f32 v[114:115], v[28:29], v[22:23] op_sel:[0,1]
	ds_read_b128 v[34:37], v69 offset:1792
	ds_read_b128 v[78:81], v69 offset:2304
	ds_read_b64 v[108:109], v118 offset:2816
	ds_read_b128 v[30:33], v69 offset:1536
	ds_read_b128 v[74:77], v69 offset:2048
	ds_read_b128 v[104:107], v69 offset:2560
	v_add_f32_dpp v110, v110, v110 row_ror:8 row_mask:0xf bank_mask:0xf bound_ctrl:1
	v_add_f32_dpp v111, v111, v111 row_ror:8 row_mask:0xf bank_mask:0xf bound_ctrl:1
	v_pk_fma_f32 v[38:39], v[0:1], v[8:9], v[38:39] op_sel_hi:[1,0,1]
	v_add_f32_dpp v110, v110, v110 row_ror:4 row_mask:0xf bank_mask:0xf bound_ctrl:1
	v_add_f32_dpp v111, v111, v111 row_ror:4 row_mask:0xf bank_mask:0xf bound_ctrl:1
	v_pk_fma_f32 v[82:83], v[2:3], v[8:9], v[82:83] op_sel:[0,1,0]
	v_add_f32_dpp v110, v110, v110 row_ror:2 row_mask:0xf bank_mask:0xf bound_ctrl:1
	v_add_f32_dpp v111, v111, v111 row_ror:2 row_mask:0xf bank_mask:0xf bound_ctrl:1
	v_pk_fma_f32 v[116:117], v[4:5], v[10:11], v[116:117] op_sel_hi:[1,0,1]
	v_add_f32_dpp v110, v110, v110 row_ror:1 row_mask:0xf bank_mask:0xf bound_ctrl:1
	v_add_f32_dpp v111, v111, v111 row_ror:1 row_mask:0xf bank_mask:0xf bound_ctrl:1
	v_pk_fma_f32 v[114:115], v[6:7], v[10:11], v[114:115] op_sel:[0,1,0]
	v_pk_fma_f32 v[0:1], v[110:111], v[16:17], v[38:39] op_sel_hi:[1,0,1]
	v_pk_fma_f32 v[2:3], v[110:111], v[16:17], v[82:83] op_sel:[0,1,0]
	v_pk_fma_f32 v[4:5], v[110:111], v[18:19], v[116:117] op_sel_hi:[1,0,1]
	v_pk_fma_f32 v[6:7], v[110:111], v[18:19], v[114:115] op_sel:[0,1,0]
	v_pk_mul_f32 v[112:113], v[0:1], v[24:25] op_sel_hi:[1,0]
	v_pk_fma_f32 v[112:113], v[2:3], v[24:25], v[112:113] op_sel:[0,1,0]
	v_pk_fma_f32 v[112:113], v[4:5], v[26:27], v[112:113] op_sel_hi:[1,0,1]
	v_pk_fma_f32 v[112:113], v[6:7], v[26:27], v[112:113] op_sel:[0,1,0]
	ds_write_b32 v119, v112 offset:0
	ds_write_b32 v119, v113 offset:64
	s_waitcnt lgkmcnt(2)
	v_pk_mul_f32 v[110:111], v[0:1], v[34:35] op_sel_hi:[1,0]
	v_pk_mul_f32 v[38:39], v[108:109], v[78:79] op_sel_hi:[1,0]
	v_pk_fma_f32 v[110:111], v[2:3], v[34:35], v[110:111] op_sel:[0,1,0]
	v_pk_mul_f32 v[82:83], v[108:109], v[78:79] op_sel:[0,1]
	v_pk_fma_f32 v[110:111], v[4:5], v[36:37], v[110:111] op_sel_hi:[1,0,1]
	v_pk_mul_f32 v[116:117], v[108:109], v[80:81] op_sel_hi:[1,0]
	v_pk_fma_f32 v[110:111], v[6:7], v[36:37], v[110:111] op_sel:[0,1,0]
	v_pk_mul_f32 v[114:115], v[108:109], v[80:81] op_sel:[0,1]
	ds_read_b128 v[12:15], v69 offset:3328
	ds_read_b128 v[20:23], v69 offset:3840
	ds_read_b64 v[28:29], v118 offset:4352
	ds_read_b128 v[8:11], v69 offset:3072
	ds_read_b128 v[16:19], v69 offset:3584
	ds_read_b128 v[24:27], v69 offset:4096
	v_add_f32_dpp v110, v110, v110 row_ror:8 row_mask:0xf bank_mask:0xf bound_ctrl:1
	v_add_f32_dpp v111, v111, v111 row_ror:8 row_mask:0xf bank_mask:0xf bound_ctrl:1
	v_pk_fma_f32 v[38:39], v[0:1], v[30:31], v[38:39] op_sel_hi:[1,0,1]
	v_add_f32_dpp v110, v110, v110 row_ror:4 row_mask:0xf bank_mask:0xf bound_ctrl:1
	v_add_f32_dpp v111, v111, v111 row_ror:4 row_mask:0xf bank_mask:0xf bound_ctrl:1
	v_pk_fma_f32 v[82:83], v[2:3], v[30:31], v[82:83] op_sel:[0,1,0]
	v_add_f32_dpp v110, v110, v110 row_ror:2 row_mask:0xf bank_mask:0xf bound_ctrl:1
	v_add_f32_dpp v111, v111, v111 row_ror:2 row_mask:0xf bank_mask:0xf bound_ctrl:1
	v_pk_fma_f32 v[116:117], v[4:5], v[32:33], v[116:117] op_sel_hi:[1,0,1]
	v_add_f32_dpp v110, v110, v110 row_ror:1 row_mask:0xf bank_mask:0xf bound_ctrl:1
	v_add_f32_dpp v111, v111, v111 row_ror:1 row_mask:0xf bank_mask:0xf bound_ctrl:1
	v_pk_fma_f32 v[114:115], v[6:7], v[32:33], v[114:115] op_sel:[0,1,0]
	v_pk_fma_f32 v[0:1], v[110:111], v[74:75], v[38:39] op_sel_hi:[1,0,1]
	v_pk_fma_f32 v[2:3], v[110:111], v[74:75], v[82:83] op_sel:[0,1,0]
	v_pk_fma_f32 v[4:5], v[110:111], v[76:77], v[116:117] op_sel_hi:[1,0,1]
	v_pk_fma_f32 v[6:7], v[110:111], v[76:77], v[114:115] op_sel:[0,1,0]
	v_pk_mul_f32 v[112:113], v[0:1], v[104:105] op_sel_hi:[1,0]
	v_pk_fma_f32 v[112:113], v[2:3], v[104:105], v[112:113] op_sel:[0,1,0]
	v_pk_fma_f32 v[112:113], v[4:5], v[106:107], v[112:113] op_sel_hi:[1,0,1]
	v_pk_fma_f32 v[112:113], v[6:7], v[106:107], v[112:113] op_sel:[0,1,0]
	ds_write_b32 v119, v112 offset:2048
	ds_write_b32 v119, v113 offset:2112
	s_waitcnt lgkmcnt(2)
	v_pk_mul_f32 v[110:111], v[0:1], v[12:13] op_sel_hi:[1,0]
	v_pk_mul_f32 v[38:39], v[28:29], v[20:21] op_sel_hi:[1,0]
	v_pk_fma_f32 v[110:111], v[2:3], v[12:13], v[110:111] op_sel:[0,1,0]
	v_pk_mul_f32 v[82:83], v[28:29], v[20:21] op_sel:[0,1]
	v_pk_fma_f32 v[110:111], v[4:5], v[14:15], v[110:111] op_sel_hi:[1,0,1]
	v_pk_mul_f32 v[116:117], v[28:29], v[22:23] op_sel_hi:[1,0]
	v_pk_fma_f32 v[110:111], v[6:7], v[14:15], v[110:111] op_sel:[0,1,0]
	v_pk_mul_f32 v[114:115], v[28:29], v[22:23] op_sel:[0,1]
	ds_read_b128 v[34:37], v69 offset:4864
	ds_read_b128 v[78:81], v69 offset:5376
	ds_read_b64 v[108:109], v118 offset:5888
	ds_read_b128 v[30:33], v69 offset:4608
	ds_read_b128 v[74:77], v69 offset:5120
	ds_read_b128 v[104:107], v69 offset:5632
	v_add_f32_dpp v110, v110, v110 row_ror:8 row_mask:0xf bank_mask:0xf bound_ctrl:1
	v_add_f32_dpp v111, v111, v111 row_ror:8 row_mask:0xf bank_mask:0xf bound_ctrl:1
	v_pk_fma_f32 v[38:39], v[0:1], v[8:9], v[38:39] op_sel_hi:[1,0,1]
	v_add_f32_dpp v110, v110, v110 row_ror:4 row_mask:0xf bank_mask:0xf bound_ctrl:1
	v_add_f32_dpp v111, v111, v111 row_ror:4 row_mask:0xf bank_mask:0xf bound_ctrl:1
	v_pk_fma_f32 v[82:83], v[2:3], v[8:9], v[82:83] op_sel:[0,1,0]
	v_add_f32_dpp v110, v110, v110 row_ror:2 row_mask:0xf bank_mask:0xf bound_ctrl:1
	v_add_f32_dpp v111, v111, v111 row_ror:2 row_mask:0xf bank_mask:0xf bound_ctrl:1
	v_pk_fma_f32 v[116:117], v[4:5], v[10:11], v[116:117] op_sel_hi:[1,0,1]
	v_add_f32_dpp v110, v110, v110 row_ror:1 row_mask:0xf bank_mask:0xf bound_ctrl:1
	v_add_f32_dpp v111, v111, v111 row_ror:1 row_mask:0xf bank_mask:0xf bound_ctrl:1
	v_pk_fma_f32 v[114:115], v[6:7], v[10:11], v[114:115] op_sel:[0,1,0]
	v_pk_fma_f32 v[0:1], v[110:111], v[16:17], v[38:39] op_sel_hi:[1,0,1]
	v_pk_fma_f32 v[2:3], v[110:111], v[16:17], v[82:83] op_sel:[0,1,0]
	v_pk_fma_f32 v[4:5], v[110:111], v[18:19], v[116:117] op_sel_hi:[1,0,1]
	v_pk_fma_f32 v[6:7], v[110:111], v[18:19], v[114:115] op_sel:[0,1,0]
	v_pk_mul_f32 v[112:113], v[0:1], v[24:25] op_sel_hi:[1,0]
	v_pk_fma_f32 v[112:113], v[2:3], v[24:25], v[112:113] op_sel:[0,1,0]
	v_pk_fma_f32 v[112:113], v[4:5], v[26:27], v[112:113] op_sel_hi:[1,0,1]
	v_pk_fma_f32 v[112:113], v[6:7], v[26:27], v[112:113] op_sel:[0,1,0]
	ds_write_b32 v119, v112 offset:4096
	ds_write_b32 v119, v113 offset:4160
	s_waitcnt lgkmcnt(2)
	v_pk_mul_f32 v[110:111], v[0:1], v[34:35] op_sel_hi:[1,0]
	v_pk_mul_f32 v[38:39], v[108:109], v[78:79] op_sel_hi:[1,0]
	v_pk_fma_f32 v[110:111], v[2:3], v[34:35], v[110:111] op_sel:[0,1,0]
	v_pk_mul_f32 v[82:83], v[108:109], v[78:79] op_sel:[0,1]
	v_pk_fma_f32 v[110:111], v[4:5], v[36:37], v[110:111] op_sel_hi:[1,0,1]
	v_pk_mul_f32 v[116:117], v[108:109], v[80:81] op_sel_hi:[1,0]
	v_pk_fma_f32 v[110:111], v[6:7], v[36:37], v[110:111] op_sel:[0,1,0]
	v_pk_mul_f32 v[114:115], v[108:109], v[80:81] op_sel:[0,1]
	ds_read_b128 v[12:15], v69 offset:6400
	ds_read_b128 v[20:23], v69 offset:6912
	ds_read_b64 v[28:29], v118 offset:7424
	ds_read_b128 v[8:11], v69 offset:6144
	ds_read_b128 v[16:19], v69 offset:6656
	ds_read_b128 v[24:27], v69 offset:7168
	v_add_f32_dpp v110, v110, v110 row_ror:8 row_mask:0xf bank_mask:0xf bound_ctrl:1
	v_add_f32_dpp v111, v111, v111 row_ror:8 row_mask:0xf bank_mask:0xf bound_ctrl:1
	v_pk_fma_f32 v[38:39], v[0:1], v[30:31], v[38:39] op_sel_hi:[1,0,1]
	v_add_f32_dpp v110, v110, v110 row_ror:4 row_mask:0xf bank_mask:0xf bound_ctrl:1
	v_add_f32_dpp v111, v111, v111 row_ror:4 row_mask:0xf bank_mask:0xf bound_ctrl:1
	v_pk_fma_f32 v[82:83], v[2:3], v[30:31], v[82:83] op_sel:[0,1,0]
	v_add_f32_dpp v110, v110, v110 row_ror:2 row_mask:0xf bank_mask:0xf bound_ctrl:1
	v_add_f32_dpp v111, v111, v111 row_ror:2 row_mask:0xf bank_mask:0xf bound_ctrl:1
	v_pk_fma_f32 v[116:117], v[4:5], v[32:33], v[116:117] op_sel_hi:[1,0,1]
	v_add_f32_dpp v110, v110, v110 row_ror:1 row_mask:0xf bank_mask:0xf bound_ctrl:1
	v_add_f32_dpp v111, v111, v111 row_ror:1 row_mask:0xf bank_mask:0xf bound_ctrl:1
	v_pk_fma_f32 v[114:115], v[6:7], v[32:33], v[114:115] op_sel:[0,1,0]
	v_pk_fma_f32 v[0:1], v[110:111], v[74:75], v[38:39] op_sel_hi:[1,0,1]
	v_pk_fma_f32 v[2:3], v[110:111], v[74:75], v[82:83] op_sel:[0,1,0]
	v_pk_fma_f32 v[4:5], v[110:111], v[76:77], v[116:117] op_sel_hi:[1,0,1]
	v_pk_fma_f32 v[6:7], v[110:111], v[76:77], v[114:115] op_sel:[0,1,0]
	v_pk_mul_f32 v[112:113], v[0:1], v[104:105] op_sel_hi:[1,0]
	v_pk_fma_f32 v[112:113], v[2:3], v[104:105], v[112:113] op_sel:[0,1,0]
	v_pk_fma_f32 v[112:113], v[4:5], v[106:107], v[112:113] op_sel_hi:[1,0,1]
	v_pk_fma_f32 v[112:113], v[6:7], v[106:107], v[112:113] op_sel:[0,1,0]
	ds_write_b32 v119, v112 offset:6144
	ds_write_b32 v119, v113 offset:6208
	s_waitcnt lgkmcnt(2)
	v_pk_mul_f32 v[110:111], v[0:1], v[12:13] op_sel_hi:[1,0]
	v_pk_mul_f32 v[38:39], v[28:29], v[20:21] op_sel_hi:[1,0]
	v_pk_fma_f32 v[110:111], v[2:3], v[12:13], v[110:111] op_sel:[0,1,0]
	v_pk_mul_f32 v[82:83], v[28:29], v[20:21] op_sel:[0,1]
	v_pk_fma_f32 v[110:111], v[4:5], v[14:15], v[110:111] op_sel_hi:[1,0,1]
	v_pk_mul_f32 v[116:117], v[28:29], v[22:23] op_sel_hi:[1,0]
	v_pk_fma_f32 v[110:111], v[6:7], v[14:15], v[110:111] op_sel:[0,1,0]
	v_pk_mul_f32 v[114:115], v[28:29], v[22:23] op_sel:[0,1]
	ds_read_b128 v[34:37], v69 offset:7936
	ds_read_b128 v[78:81], v69 offset:8448
	ds_read_b64 v[108:109], v118 offset:8960
	ds_read_b128 v[30:33], v69 offset:7680
	ds_read_b128 v[74:77], v69 offset:8192
	ds_read_b128 v[104:107], v69 offset:8704
	v_add_f32_dpp v110, v110, v110 row_ror:8 row_mask:0xf bank_mask:0xf bound_ctrl:1
	v_add_f32_dpp v111, v111, v111 row_ror:8 row_mask:0xf bank_mask:0xf bound_ctrl:1
	v_pk_fma_f32 v[38:39], v[0:1], v[8:9], v[38:39] op_sel_hi:[1,0,1]
	v_add_f32_dpp v110, v110, v110 row_ror:4 row_mask:0xf bank_mask:0xf bound_ctrl:1
	v_add_f32_dpp v111, v111, v111 row_ror:4 row_mask:0xf bank_mask:0xf bound_ctrl:1
	v_pk_fma_f32 v[82:83], v[2:3], v[8:9], v[82:83] op_sel:[0,1,0]
	v_add_f32_dpp v110, v110, v110 row_ror:2 row_mask:0xf bank_mask:0xf bound_ctrl:1
	v_add_f32_dpp v111, v111, v111 row_ror:2 row_mask:0xf bank_mask:0xf bound_ctrl:1
	v_pk_fma_f32 v[116:117], v[4:5], v[10:11], v[116:117] op_sel_hi:[1,0,1]
	v_add_f32_dpp v110, v110, v110 row_ror:1 row_mask:0xf bank_mask:0xf bound_ctrl:1
	v_add_f32_dpp v111, v111, v111 row_ror:1 row_mask:0xf bank_mask:0xf bound_ctrl:1
	v_pk_fma_f32 v[114:115], v[6:7], v[10:11], v[114:115] op_sel:[0,1,0]
	v_pk_fma_f32 v[0:1], v[110:111], v[16:17], v[38:39] op_sel_hi:[1,0,1]
	v_pk_fma_f32 v[2:3], v[110:111], v[16:17], v[82:83] op_sel:[0,1,0]
	v_pk_fma_f32 v[4:5], v[110:111], v[18:19], v[116:117] op_sel_hi:[1,0,1]
	v_pk_fma_f32 v[6:7], v[110:111], v[18:19], v[114:115] op_sel:[0,1,0]
	v_pk_mul_f32 v[112:113], v[0:1], v[24:25] op_sel_hi:[1,0]
	v_pk_fma_f32 v[112:113], v[2:3], v[24:25], v[112:113] op_sel:[0,1,0]
	v_pk_fma_f32 v[112:113], v[4:5], v[26:27], v[112:113] op_sel_hi:[1,0,1]
	v_pk_fma_f32 v[112:113], v[6:7], v[26:27], v[112:113] op_sel:[0,1,0]
	ds_write_b32 v119, v112 offset:8192
	ds_write_b32 v119, v113 offset:8256
	s_waitcnt lgkmcnt(2)
	v_pk_mul_f32 v[110:111], v[0:1], v[34:35] op_sel_hi:[1,0]
	v_pk_mul_f32 v[38:39], v[108:109], v[78:79] op_sel_hi:[1,0]
	v_pk_fma_f32 v[110:111], v[2:3], v[34:35], v[110:111] op_sel:[0,1,0]
	v_pk_mul_f32 v[82:83], v[108:109], v[78:79] op_sel:[0,1]
	v_pk_fma_f32 v[110:111], v[4:5], v[36:37], v[110:111] op_sel_hi:[1,0,1]
	v_pk_mul_f32 v[116:117], v[108:109], v[80:81] op_sel_hi:[1,0]
	v_pk_fma_f32 v[110:111], v[6:7], v[36:37], v[110:111] op_sel:[0,1,0]
	v_pk_mul_f32 v[114:115], v[108:109], v[80:81] op_sel:[0,1]
	ds_read_b128 v[12:15], v69 offset:9472
	ds_read_b128 v[20:23], v69 offset:9984
	ds_read_b64 v[28:29], v118 offset:10496
	ds_read_b128 v[8:11], v69 offset:9216
	ds_read_b128 v[16:19], v69 offset:9728
	ds_read_b128 v[24:27], v69 offset:10240
	v_add_f32_dpp v110, v110, v110 row_ror:8 row_mask:0xf bank_mask:0xf bound_ctrl:1
	v_add_f32_dpp v111, v111, v111 row_ror:8 row_mask:0xf bank_mask:0xf bound_ctrl:1
	v_pk_fma_f32 v[38:39], v[0:1], v[30:31], v[38:39] op_sel_hi:[1,0,1]
	v_add_f32_dpp v110, v110, v110 row_ror:4 row_mask:0xf bank_mask:0xf bound_ctrl:1
	v_add_f32_dpp v111, v111, v111 row_ror:4 row_mask:0xf bank_mask:0xf bound_ctrl:1
	v_pk_fma_f32 v[82:83], v[2:3], v[30:31], v[82:83] op_sel:[0,1,0]
	v_add_f32_dpp v110, v110, v110 row_ror:2 row_mask:0xf bank_mask:0xf bound_ctrl:1
	v_add_f32_dpp v111, v111, v111 row_ror:2 row_mask:0xf bank_mask:0xf bound_ctrl:1
	v_pk_fma_f32 v[116:117], v[4:5], v[32:33], v[116:117] op_sel_hi:[1,0,1]
	v_add_f32_dpp v110, v110, v110 row_ror:1 row_mask:0xf bank_mask:0xf bound_ctrl:1
	v_add_f32_dpp v111, v111, v111 row_ror:1 row_mask:0xf bank_mask:0xf bound_ctrl:1
	v_pk_fma_f32 v[114:115], v[6:7], v[32:33], v[114:115] op_sel:[0,1,0]
	v_pk_fma_f32 v[0:1], v[110:111], v[74:75], v[38:39] op_sel_hi:[1,0,1]
	v_pk_fma_f32 v[2:3], v[110:111], v[74:75], v[82:83] op_sel:[0,1,0]
	v_pk_fma_f32 v[4:5], v[110:111], v[76:77], v[116:117] op_sel_hi:[1,0,1]
	v_pk_fma_f32 v[6:7], v[110:111], v[76:77], v[114:115] op_sel:[0,1,0]
	v_pk_mul_f32 v[112:113], v[0:1], v[104:105] op_sel_hi:[1,0]
	v_pk_fma_f32 v[112:113], v[2:3], v[104:105], v[112:113] op_sel:[0,1,0]
	v_pk_fma_f32 v[112:113], v[4:5], v[106:107], v[112:113] op_sel_hi:[1,0,1]
	v_pk_fma_f32 v[112:113], v[6:7], v[106:107], v[112:113] op_sel:[0,1,0]
	ds_write_b32 v119, v112 offset:10240
	ds_write_b32 v119, v113 offset:10304
	s_waitcnt lgkmcnt(2)
	v_pk_mul_f32 v[110:111], v[0:1], v[12:13] op_sel_hi:[1,0]
	v_pk_mul_f32 v[38:39], v[28:29], v[20:21] op_sel_hi:[1,0]
	v_pk_fma_f32 v[110:111], v[2:3], v[12:13], v[110:111] op_sel:[0,1,0]
	v_pk_mul_f32 v[82:83], v[28:29], v[20:21] op_sel:[0,1]
	v_pk_fma_f32 v[110:111], v[4:5], v[14:15], v[110:111] op_sel_hi:[1,0,1]
	v_pk_mul_f32 v[116:117], v[28:29], v[22:23] op_sel_hi:[1,0]
	v_pk_fma_f32 v[110:111], v[6:7], v[14:15], v[110:111] op_sel:[0,1,0]
	v_pk_mul_f32 v[114:115], v[28:29], v[22:23] op_sel:[0,1]
	ds_read_b128 v[34:37], v69 offset:11008
	ds_read_b128 v[78:81], v69 offset:11520
	ds_read_b64 v[108:109], v118 offset:12032
	ds_read_b128 v[30:33], v69 offset:10752
	ds_read_b128 v[74:77], v69 offset:11264
	ds_read_b128 v[104:107], v69 offset:11776
	v_add_f32_dpp v110, v110, v110 row_ror:8 row_mask:0xf bank_mask:0xf bound_ctrl:1
	v_add_f32_dpp v111, v111, v111 row_ror:8 row_mask:0xf bank_mask:0xf bound_ctrl:1
	v_pk_fma_f32 v[38:39], v[0:1], v[8:9], v[38:39] op_sel_hi:[1,0,1]
	v_add_f32_dpp v110, v110, v110 row_ror:4 row_mask:0xf bank_mask:0xf bound_ctrl:1
	v_add_f32_dpp v111, v111, v111 row_ror:4 row_mask:0xf bank_mask:0xf bound_ctrl:1
	v_pk_fma_f32 v[82:83], v[2:3], v[8:9], v[82:83] op_sel:[0,1,0]
	v_add_f32_dpp v110, v110, v110 row_ror:2 row_mask:0xf bank_mask:0xf bound_ctrl:1
	v_add_f32_dpp v111, v111, v111 row_ror:2 row_mask:0xf bank_mask:0xf bound_ctrl:1
	v_pk_fma_f32 v[116:117], v[4:5], v[10:11], v[116:117] op_sel_hi:[1,0,1]
	v_add_f32_dpp v110, v110, v110 row_ror:1 row_mask:0xf bank_mask:0xf bound_ctrl:1
	v_add_f32_dpp v111, v111, v111 row_ror:1 row_mask:0xf bank_mask:0xf bound_ctrl:1
	v_pk_fma_f32 v[114:115], v[6:7], v[10:11], v[114:115] op_sel:[0,1,0]
	v_pk_fma_f32 v[0:1], v[110:111], v[16:17], v[38:39] op_sel_hi:[1,0,1]
	v_pk_fma_f32 v[2:3], v[110:111], v[16:17], v[82:83] op_sel:[0,1,0]
	v_pk_fma_f32 v[4:5], v[110:111], v[18:19], v[116:117] op_sel_hi:[1,0,1]
	v_pk_fma_f32 v[6:7], v[110:111], v[18:19], v[114:115] op_sel:[0,1,0]
	v_pk_mul_f32 v[112:113], v[0:1], v[24:25] op_sel_hi:[1,0]
	v_pk_fma_f32 v[112:113], v[2:3], v[24:25], v[112:113] op_sel:[0,1,0]
	v_pk_fma_f32 v[112:113], v[4:5], v[26:27], v[112:113] op_sel_hi:[1,0,1]
	v_pk_fma_f32 v[112:113], v[6:7], v[26:27], v[112:113] op_sel:[0,1,0]
	ds_write_b32 v119, v112 offset:12288
	ds_write_b32 v119, v113 offset:12352
	s_waitcnt lgkmcnt(2)
	v_pk_mul_f32 v[110:111], v[0:1], v[34:35] op_sel_hi:[1,0]
	v_pk_mul_f32 v[38:39], v[108:109], v[78:79] op_sel_hi:[1,0]
	v_pk_fma_f32 v[110:111], v[2:3], v[34:35], v[110:111] op_sel:[0,1,0]
	v_pk_mul_f32 v[82:83], v[108:109], v[78:79] op_sel:[0,1]
	v_pk_fma_f32 v[110:111], v[4:5], v[36:37], v[110:111] op_sel_hi:[1,0,1]
	v_pk_mul_f32 v[116:117], v[108:109], v[80:81] op_sel_hi:[1,0]
	v_pk_fma_f32 v[110:111], v[6:7], v[36:37], v[110:111] op_sel:[0,1,0]
	v_pk_mul_f32 v[114:115], v[108:109], v[80:81] op_sel:[0,1]
	ds_read_b128 v[12:15], v69 offset:12544
	ds_read_b128 v[20:23], v69 offset:13056
	ds_read_b64 v[28:29], v118 offset:13568
	ds_read_b128 v[8:11], v69 offset:12288
	ds_read_b128 v[16:19], v69 offset:12800
	ds_read_b128 v[24:27], v69 offset:13312
	v_add_f32_dpp v110, v110, v110 row_ror:8 row_mask:0xf bank_mask:0xf bound_ctrl:1
	v_add_f32_dpp v111, v111, v111 row_ror:8 row_mask:0xf bank_mask:0xf bound_ctrl:1
	v_pk_fma_f32 v[38:39], v[0:1], v[30:31], v[38:39] op_sel_hi:[1,0,1]
	v_add_f32_dpp v110, v110, v110 row_ror:4 row_mask:0xf bank_mask:0xf bound_ctrl:1
	v_add_f32_dpp v111, v111, v111 row_ror:4 row_mask:0xf bank_mask:0xf bound_ctrl:1
	v_pk_fma_f32 v[82:83], v[2:3], v[30:31], v[82:83] op_sel:[0,1,0]
	v_add_f32_dpp v110, v110, v110 row_ror:2 row_mask:0xf bank_mask:0xf bound_ctrl:1
	v_add_f32_dpp v111, v111, v111 row_ror:2 row_mask:0xf bank_mask:0xf bound_ctrl:1
	v_pk_fma_f32 v[116:117], v[4:5], v[32:33], v[116:117] op_sel_hi:[1,0,1]
	v_add_f32_dpp v110, v110, v110 row_ror:1 row_mask:0xf bank_mask:0xf bound_ctrl:1
	v_add_f32_dpp v111, v111, v111 row_ror:1 row_mask:0xf bank_mask:0xf bound_ctrl:1
	v_pk_fma_f32 v[114:115], v[6:7], v[32:33], v[114:115] op_sel:[0,1,0]
	v_pk_fma_f32 v[0:1], v[110:111], v[74:75], v[38:39] op_sel_hi:[1,0,1]
	v_pk_fma_f32 v[2:3], v[110:111], v[74:75], v[82:83] op_sel:[0,1,0]
	v_pk_fma_f32 v[4:5], v[110:111], v[76:77], v[116:117] op_sel_hi:[1,0,1]
	v_pk_fma_f32 v[6:7], v[110:111], v[76:77], v[114:115] op_sel:[0,1,0]
	v_pk_mul_f32 v[112:113], v[0:1], v[104:105] op_sel_hi:[1,0]
	v_pk_fma_f32 v[112:113], v[2:3], v[104:105], v[112:113] op_sel:[0,1,0]
	v_pk_fma_f32 v[112:113], v[4:5], v[106:107], v[112:113] op_sel_hi:[1,0,1]
	v_pk_fma_f32 v[112:113], v[6:7], v[106:107], v[112:113] op_sel:[0,1,0]
	ds_write_b32 v119, v112 offset:14336
	ds_write_b32 v119, v113 offset:14400
	s_waitcnt lgkmcnt(2)
	v_pk_mul_f32 v[110:111], v[0:1], v[12:13] op_sel_hi:[1,0]
	v_pk_mul_f32 v[38:39], v[28:29], v[20:21] op_sel_hi:[1,0]
	v_pk_fma_f32 v[110:111], v[2:3], v[12:13], v[110:111] op_sel:[0,1,0]
	v_pk_mul_f32 v[82:83], v[28:29], v[20:21] op_sel:[0,1]
	v_pk_fma_f32 v[110:111], v[4:5], v[14:15], v[110:111] op_sel_hi:[1,0,1]
	v_pk_mul_f32 v[116:117], v[28:29], v[22:23] op_sel_hi:[1,0]
	v_pk_fma_f32 v[110:111], v[6:7], v[14:15], v[110:111] op_sel:[0,1,0]
	v_pk_mul_f32 v[114:115], v[28:29], v[22:23] op_sel:[0,1]
	ds_read_b128 v[34:37], v69 offset:14080
	ds_read_b128 v[78:81], v69 offset:14592
	ds_read_b64 v[108:109], v118 offset:15104
	ds_read_b128 v[30:33], v69 offset:13824
	ds_read_b128 v[74:77], v69 offset:14336
	ds_read_b128 v[104:107], v69 offset:14848
	v_add_f32_dpp v110, v110, v110 row_ror:8 row_mask:0xf bank_mask:0xf bound_ctrl:1
	v_add_f32_dpp v111, v111, v111 row_ror:8 row_mask:0xf bank_mask:0xf bound_ctrl:1
	v_pk_fma_f32 v[38:39], v[0:1], v[8:9], v[38:39] op_sel_hi:[1,0,1]
	v_add_f32_dpp v110, v110, v110 row_ror:4 row_mask:0xf bank_mask:0xf bound_ctrl:1
	v_add_f32_dpp v111, v111, v111 row_ror:4 row_mask:0xf bank_mask:0xf bound_ctrl:1
	v_pk_fma_f32 v[82:83], v[2:3], v[8:9], v[82:83] op_sel:[0,1,0]
	v_add_f32_dpp v110, v110, v110 row_ror:2 row_mask:0xf bank_mask:0xf bound_ctrl:1
	v_add_f32_dpp v111, v111, v111 row_ror:2 row_mask:0xf bank_mask:0xf bound_ctrl:1
	v_pk_fma_f32 v[116:117], v[4:5], v[10:11], v[116:117] op_sel_hi:[1,0,1]
	v_add_f32_dpp v110, v110, v110 row_ror:1 row_mask:0xf bank_mask:0xf bound_ctrl:1
	v_add_f32_dpp v111, v111, v111 row_ror:1 row_mask:0xf bank_mask:0xf bound_ctrl:1
	v_pk_fma_f32 v[114:115], v[6:7], v[10:11], v[114:115] op_sel:[0,1,0]
	v_pk_fma_f32 v[0:1], v[110:111], v[16:17], v[38:39] op_sel_hi:[1,0,1]
	v_pk_fma_f32 v[2:3], v[110:111], v[16:17], v[82:83] op_sel:[0,1,0]
	v_pk_fma_f32 v[4:5], v[110:111], v[18:19], v[116:117] op_sel_hi:[1,0,1]
	v_pk_fma_f32 v[6:7], v[110:111], v[18:19], v[114:115] op_sel:[0,1,0]
	v_pk_mul_f32 v[112:113], v[0:1], v[24:25] op_sel_hi:[1,0]
	v_pk_fma_f32 v[112:113], v[2:3], v[24:25], v[112:113] op_sel:[0,1,0]
	v_pk_fma_f32 v[112:113], v[4:5], v[26:27], v[112:113] op_sel_hi:[1,0,1]
	v_pk_fma_f32 v[112:113], v[6:7], v[26:27], v[112:113] op_sel:[0,1,0]
	ds_write_b32 v119, v112 offset:16384
	ds_write_b32 v119, v113 offset:16448
	s_waitcnt lgkmcnt(2)
	v_pk_mul_f32 v[110:111], v[0:1], v[34:35] op_sel_hi:[1,0]
	v_pk_mul_f32 v[38:39], v[108:109], v[78:79] op_sel_hi:[1,0]
	v_pk_fma_f32 v[110:111], v[2:3], v[34:35], v[110:111] op_sel:[0,1,0]
	v_pk_mul_f32 v[82:83], v[108:109], v[78:79] op_sel:[0,1]
	v_pk_fma_f32 v[110:111], v[4:5], v[36:37], v[110:111] op_sel_hi:[1,0,1]
	v_pk_mul_f32 v[116:117], v[108:109], v[80:81] op_sel_hi:[1,0]
	v_pk_fma_f32 v[110:111], v[6:7], v[36:37], v[110:111] op_sel:[0,1,0]
	v_pk_mul_f32 v[114:115], v[108:109], v[80:81] op_sel:[0,1]
	ds_read_b128 v[12:15], v69 offset:15616
	ds_read_b128 v[20:23], v69 offset:16128
	ds_read_b64 v[28:29], v118 offset:16640
	ds_read_b128 v[8:11], v69 offset:15360
	ds_read_b128 v[16:19], v69 offset:15872
	ds_read_b128 v[24:27], v69 offset:16384
	v_add_f32_dpp v110, v110, v110 row_ror:8 row_mask:0xf bank_mask:0xf bound_ctrl:1
	v_add_f32_dpp v111, v111, v111 row_ror:8 row_mask:0xf bank_mask:0xf bound_ctrl:1
	v_pk_fma_f32 v[38:39], v[0:1], v[30:31], v[38:39] op_sel_hi:[1,0,1]
	v_add_f32_dpp v110, v110, v110 row_ror:4 row_mask:0xf bank_mask:0xf bound_ctrl:1
	v_add_f32_dpp v111, v111, v111 row_ror:4 row_mask:0xf bank_mask:0xf bound_ctrl:1
	v_pk_fma_f32 v[82:83], v[2:3], v[30:31], v[82:83] op_sel:[0,1,0]
	v_add_f32_dpp v110, v110, v110 row_ror:2 row_mask:0xf bank_mask:0xf bound_ctrl:1
	v_add_f32_dpp v111, v111, v111 row_ror:2 row_mask:0xf bank_mask:0xf bound_ctrl:1
	v_pk_fma_f32 v[116:117], v[4:5], v[32:33], v[116:117] op_sel_hi:[1,0,1]
	v_add_f32_dpp v110, v110, v110 row_ror:1 row_mask:0xf bank_mask:0xf bound_ctrl:1
	v_add_f32_dpp v111, v111, v111 row_ror:1 row_mask:0xf bank_mask:0xf bound_ctrl:1
	v_pk_fma_f32 v[114:115], v[6:7], v[32:33], v[114:115] op_sel:[0,1,0]
	v_pk_fma_f32 v[0:1], v[110:111], v[74:75], v[38:39] op_sel_hi:[1,0,1]
	v_pk_fma_f32 v[2:3], v[110:111], v[74:75], v[82:83] op_sel:[0,1,0]
	v_pk_fma_f32 v[4:5], v[110:111], v[76:77], v[116:117] op_sel_hi:[1,0,1]
	v_pk_fma_f32 v[6:7], v[110:111], v[76:77], v[114:115] op_sel:[0,1,0]
	v_pk_mul_f32 v[112:113], v[0:1], v[104:105] op_sel_hi:[1,0]
	v_pk_fma_f32 v[112:113], v[2:3], v[104:105], v[112:113] op_sel:[0,1,0]
	v_pk_fma_f32 v[112:113], v[4:5], v[106:107], v[112:113] op_sel_hi:[1,0,1]
	v_pk_fma_f32 v[112:113], v[6:7], v[106:107], v[112:113] op_sel:[0,1,0]
	ds_write_b32 v119, v112 offset:18432
	ds_write_b32 v119, v113 offset:18496
	s_waitcnt lgkmcnt(2)
	v_pk_mul_f32 v[110:111], v[0:1], v[12:13] op_sel_hi:[1,0]
	v_pk_mul_f32 v[38:39], v[28:29], v[20:21] op_sel_hi:[1,0]
	v_pk_fma_f32 v[110:111], v[2:3], v[12:13], v[110:111] op_sel:[0,1,0]
	v_pk_mul_f32 v[82:83], v[28:29], v[20:21] op_sel:[0,1]
	v_pk_fma_f32 v[110:111], v[4:5], v[14:15], v[110:111] op_sel_hi:[1,0,1]
	v_pk_mul_f32 v[116:117], v[28:29], v[22:23] op_sel_hi:[1,0]
	v_pk_fma_f32 v[110:111], v[6:7], v[14:15], v[110:111] op_sel:[0,1,0]
	v_pk_mul_f32 v[114:115], v[28:29], v[22:23] op_sel:[0,1]
	ds_read_b128 v[34:37], v69 offset:17152
	ds_read_b128 v[78:81], v69 offset:17664
	ds_read_b64 v[108:109], v118 offset:18176
	ds_read_b128 v[30:33], v69 offset:16896
	ds_read_b128 v[74:77], v69 offset:17408
	ds_read_b128 v[104:107], v69 offset:17920
	v_add_f32_dpp v110, v110, v110 row_ror:8 row_mask:0xf bank_mask:0xf bound_ctrl:1
	v_add_f32_dpp v111, v111, v111 row_ror:8 row_mask:0xf bank_mask:0xf bound_ctrl:1
	v_pk_fma_f32 v[38:39], v[0:1], v[8:9], v[38:39] op_sel_hi:[1,0,1]
	v_add_f32_dpp v110, v110, v110 row_ror:4 row_mask:0xf bank_mask:0xf bound_ctrl:1
	v_add_f32_dpp v111, v111, v111 row_ror:4 row_mask:0xf bank_mask:0xf bound_ctrl:1
	v_pk_fma_f32 v[82:83], v[2:3], v[8:9], v[82:83] op_sel:[0,1,0]
	v_add_f32_dpp v110, v110, v110 row_ror:2 row_mask:0xf bank_mask:0xf bound_ctrl:1
	v_add_f32_dpp v111, v111, v111 row_ror:2 row_mask:0xf bank_mask:0xf bound_ctrl:1
	v_pk_fma_f32 v[116:117], v[4:5], v[10:11], v[116:117] op_sel_hi:[1,0,1]
	v_add_f32_dpp v110, v110, v110 row_ror:1 row_mask:0xf bank_mask:0xf bound_ctrl:1
	v_add_f32_dpp v111, v111, v111 row_ror:1 row_mask:0xf bank_mask:0xf bound_ctrl:1
	v_pk_fma_f32 v[114:115], v[6:7], v[10:11], v[114:115] op_sel:[0,1,0]
	v_pk_fma_f32 v[0:1], v[110:111], v[16:17], v[38:39] op_sel_hi:[1,0,1]
	v_pk_fma_f32 v[2:3], v[110:111], v[16:17], v[82:83] op_sel:[0,1,0]
	v_pk_fma_f32 v[4:5], v[110:111], v[18:19], v[116:117] op_sel_hi:[1,0,1]
	v_pk_fma_f32 v[6:7], v[110:111], v[18:19], v[114:115] op_sel:[0,1,0]
	v_pk_mul_f32 v[112:113], v[0:1], v[24:25] op_sel_hi:[1,0]
	v_pk_fma_f32 v[112:113], v[2:3], v[24:25], v[112:113] op_sel:[0,1,0]
	v_pk_fma_f32 v[112:113], v[4:5], v[26:27], v[112:113] op_sel_hi:[1,0,1]
	v_pk_fma_f32 v[112:113], v[6:7], v[26:27], v[112:113] op_sel:[0,1,0]
	ds_write_b32 v119, v112 offset:20480
	ds_write_b32 v119, v113 offset:20544
	s_waitcnt lgkmcnt(2)
	v_pk_mul_f32 v[110:111], v[0:1], v[34:35] op_sel_hi:[1,0]
	v_pk_mul_f32 v[38:39], v[108:109], v[78:79] op_sel_hi:[1,0]
	v_pk_fma_f32 v[110:111], v[2:3], v[34:35], v[110:111] op_sel:[0,1,0]
	v_pk_mul_f32 v[82:83], v[108:109], v[78:79] op_sel:[0,1]
	v_pk_fma_f32 v[110:111], v[4:5], v[36:37], v[110:111] op_sel_hi:[1,0,1]
	v_pk_mul_f32 v[116:117], v[108:109], v[80:81] op_sel_hi:[1,0]
	v_pk_fma_f32 v[110:111], v[6:7], v[36:37], v[110:111] op_sel:[0,1,0]
	v_pk_mul_f32 v[114:115], v[108:109], v[80:81] op_sel:[0,1]
	ds_read_b128 v[12:15], v69 offset:18688
	ds_read_b128 v[20:23], v69 offset:19200
	ds_read_b64 v[28:29], v118 offset:19712
	ds_read_b128 v[8:11], v69 offset:18432
	ds_read_b128 v[16:19], v69 offset:18944
	ds_read_b128 v[24:27], v69 offset:19456
	v_add_f32_dpp v110, v110, v110 row_ror:8 row_mask:0xf bank_mask:0xf bound_ctrl:1
	v_add_f32_dpp v111, v111, v111 row_ror:8 row_mask:0xf bank_mask:0xf bound_ctrl:1
	v_pk_fma_f32 v[38:39], v[0:1], v[30:31], v[38:39] op_sel_hi:[1,0,1]
	v_add_f32_dpp v110, v110, v110 row_ror:4 row_mask:0xf bank_mask:0xf bound_ctrl:1
	v_add_f32_dpp v111, v111, v111 row_ror:4 row_mask:0xf bank_mask:0xf bound_ctrl:1
	v_pk_fma_f32 v[82:83], v[2:3], v[30:31], v[82:83] op_sel:[0,1,0]
	v_add_f32_dpp v110, v110, v110 row_ror:2 row_mask:0xf bank_mask:0xf bound_ctrl:1
	v_add_f32_dpp v111, v111, v111 row_ror:2 row_mask:0xf bank_mask:0xf bound_ctrl:1
	v_pk_fma_f32 v[116:117], v[4:5], v[32:33], v[116:117] op_sel_hi:[1,0,1]
	v_add_f32_dpp v110, v110, v110 row_ror:1 row_mask:0xf bank_mask:0xf bound_ctrl:1
	v_add_f32_dpp v111, v111, v111 row_ror:1 row_mask:0xf bank_mask:0xf bound_ctrl:1
	v_pk_fma_f32 v[114:115], v[6:7], v[32:33], v[114:115] op_sel:[0,1,0]
	v_pk_fma_f32 v[0:1], v[110:111], v[74:75], v[38:39] op_sel_hi:[1,0,1]
	v_pk_fma_f32 v[2:3], v[110:111], v[74:75], v[82:83] op_sel:[0,1,0]
	v_pk_fma_f32 v[4:5], v[110:111], v[76:77], v[116:117] op_sel_hi:[1,0,1]
	v_pk_fma_f32 v[6:7], v[110:111], v[76:77], v[114:115] op_sel:[0,1,0]
	v_pk_mul_f32 v[112:113], v[0:1], v[104:105] op_sel_hi:[1,0]
	v_pk_fma_f32 v[112:113], v[2:3], v[104:105], v[112:113] op_sel:[0,1,0]
	v_pk_fma_f32 v[112:113], v[4:5], v[106:107], v[112:113] op_sel_hi:[1,0,1]
	v_pk_fma_f32 v[112:113], v[6:7], v[106:107], v[112:113] op_sel:[0,1,0]
	ds_write_b32 v119, v112 offset:22528
	ds_write_b32 v119, v113 offset:22592
	s_waitcnt lgkmcnt(2)
	v_pk_mul_f32 v[110:111], v[0:1], v[12:13] op_sel_hi:[1,0]
	v_pk_mul_f32 v[38:39], v[28:29], v[20:21] op_sel_hi:[1,0]
	v_pk_fma_f32 v[110:111], v[2:3], v[12:13], v[110:111] op_sel:[0,1,0]
	v_pk_mul_f32 v[82:83], v[28:29], v[20:21] op_sel:[0,1]
	v_pk_fma_f32 v[110:111], v[4:5], v[14:15], v[110:111] op_sel_hi:[1,0,1]
	v_pk_mul_f32 v[116:117], v[28:29], v[22:23] op_sel_hi:[1,0]
	v_pk_fma_f32 v[110:111], v[6:7], v[14:15], v[110:111] op_sel:[0,1,0]
	v_pk_mul_f32 v[114:115], v[28:29], v[22:23] op_sel:[0,1]
	ds_read_b128 v[34:37], v69 offset:20224
	ds_read_b128 v[78:81], v69 offset:20736
	ds_read_b64 v[108:109], v118 offset:21248
	ds_read_b128 v[30:33], v69 offset:19968
	ds_read_b128 v[74:77], v69 offset:20480
	ds_read_b128 v[104:107], v69 offset:20992
	v_add_f32_dpp v110, v110, v110 row_ror:8 row_mask:0xf bank_mask:0xf bound_ctrl:1
	v_add_f32_dpp v111, v111, v111 row_ror:8 row_mask:0xf bank_mask:0xf bound_ctrl:1
	v_pk_fma_f32 v[38:39], v[0:1], v[8:9], v[38:39] op_sel_hi:[1,0,1]
	v_add_f32_dpp v110, v110, v110 row_ror:4 row_mask:0xf bank_mask:0xf bound_ctrl:1
	v_add_f32_dpp v111, v111, v111 row_ror:4 row_mask:0xf bank_mask:0xf bound_ctrl:1
	v_pk_fma_f32 v[82:83], v[2:3], v[8:9], v[82:83] op_sel:[0,1,0]
	v_add_f32_dpp v110, v110, v110 row_ror:2 row_mask:0xf bank_mask:0xf bound_ctrl:1
	v_add_f32_dpp v111, v111, v111 row_ror:2 row_mask:0xf bank_mask:0xf bound_ctrl:1
	v_pk_fma_f32 v[116:117], v[4:5], v[10:11], v[116:117] op_sel_hi:[1,0,1]
	v_add_f32_dpp v110, v110, v110 row_ror:1 row_mask:0xf bank_mask:0xf bound_ctrl:1
	v_add_f32_dpp v111, v111, v111 row_ror:1 row_mask:0xf bank_mask:0xf bound_ctrl:1
	v_pk_fma_f32 v[114:115], v[6:7], v[10:11], v[114:115] op_sel:[0,1,0]
	v_pk_fma_f32 v[0:1], v[110:111], v[16:17], v[38:39] op_sel_hi:[1,0,1]
	v_pk_fma_f32 v[2:3], v[110:111], v[16:17], v[82:83] op_sel:[0,1,0]
	v_pk_fma_f32 v[4:5], v[110:111], v[18:19], v[116:117] op_sel_hi:[1,0,1]
	v_pk_fma_f32 v[6:7], v[110:111], v[18:19], v[114:115] op_sel:[0,1,0]
	v_pk_mul_f32 v[112:113], v[0:1], v[24:25] op_sel_hi:[1,0]
	v_pk_fma_f32 v[112:113], v[2:3], v[24:25], v[112:113] op_sel:[0,1,0]
	v_pk_fma_f32 v[112:113], v[4:5], v[26:27], v[112:113] op_sel_hi:[1,0,1]
	v_pk_fma_f32 v[112:113], v[6:7], v[26:27], v[112:113] op_sel:[0,1,0]
	ds_write_b32 v119, v112 offset:24576
	ds_write_b32 v119, v113 offset:24640
	s_waitcnt lgkmcnt(2)
	v_pk_mul_f32 v[110:111], v[0:1], v[34:35] op_sel_hi:[1,0]
	v_pk_mul_f32 v[38:39], v[108:109], v[78:79] op_sel_hi:[1,0]
	v_pk_fma_f32 v[110:111], v[2:3], v[34:35], v[110:111] op_sel:[0,1,0]
	v_pk_mul_f32 v[82:83], v[108:109], v[78:79] op_sel:[0,1]
	v_pk_fma_f32 v[110:111], v[4:5], v[36:37], v[110:111] op_sel_hi:[1,0,1]
	v_pk_mul_f32 v[116:117], v[108:109], v[80:81] op_sel_hi:[1,0]
	v_pk_fma_f32 v[110:111], v[6:7], v[36:37], v[110:111] op_sel:[0,1,0]
	v_pk_mul_f32 v[114:115], v[108:109], v[80:81] op_sel:[0,1]
	ds_read_b128 v[12:15], v69 offset:21760
	ds_read_b128 v[20:23], v69 offset:22272
	ds_read_b64 v[28:29], v118 offset:22784
	ds_read_b128 v[8:11], v69 offset:21504
	ds_read_b128 v[16:19], v69 offset:22016
	ds_read_b128 v[24:27], v69 offset:22528
	v_add_f32_dpp v110, v110, v110 row_ror:8 row_mask:0xf bank_mask:0xf bound_ctrl:1
	v_add_f32_dpp v111, v111, v111 row_ror:8 row_mask:0xf bank_mask:0xf bound_ctrl:1
	v_pk_fma_f32 v[38:39], v[0:1], v[30:31], v[38:39] op_sel_hi:[1,0,1]
	v_add_f32_dpp v110, v110, v110 row_ror:4 row_mask:0xf bank_mask:0xf bound_ctrl:1
	v_add_f32_dpp v111, v111, v111 row_ror:4 row_mask:0xf bank_mask:0xf bound_ctrl:1
	v_pk_fma_f32 v[82:83], v[2:3], v[30:31], v[82:83] op_sel:[0,1,0]
	v_add_f32_dpp v110, v110, v110 row_ror:2 row_mask:0xf bank_mask:0xf bound_ctrl:1
	v_add_f32_dpp v111, v111, v111 row_ror:2 row_mask:0xf bank_mask:0xf bound_ctrl:1
	v_pk_fma_f32 v[116:117], v[4:5], v[32:33], v[116:117] op_sel_hi:[1,0,1]
	v_add_f32_dpp v110, v110, v110 row_ror:1 row_mask:0xf bank_mask:0xf bound_ctrl:1
	v_add_f32_dpp v111, v111, v111 row_ror:1 row_mask:0xf bank_mask:0xf bound_ctrl:1
	v_pk_fma_f32 v[114:115], v[6:7], v[32:33], v[114:115] op_sel:[0,1,0]
	v_pk_fma_f32 v[0:1], v[110:111], v[74:75], v[38:39] op_sel_hi:[1,0,1]
	v_pk_fma_f32 v[2:3], v[110:111], v[74:75], v[82:83] op_sel:[0,1,0]
	v_pk_fma_f32 v[4:5], v[110:111], v[76:77], v[116:117] op_sel_hi:[1,0,1]
	v_pk_fma_f32 v[6:7], v[110:111], v[76:77], v[114:115] op_sel:[0,1,0]
	v_pk_mul_f32 v[112:113], v[0:1], v[104:105] op_sel_hi:[1,0]
	v_pk_fma_f32 v[112:113], v[2:3], v[104:105], v[112:113] op_sel:[0,1,0]
	v_pk_fma_f32 v[112:113], v[4:5], v[106:107], v[112:113] op_sel_hi:[1,0,1]
	v_pk_fma_f32 v[112:113], v[6:7], v[106:107], v[112:113] op_sel:[0,1,0]
	ds_write_b32 v119, v112 offset:26624
	ds_write_b32 v119, v113 offset:26688
	s_waitcnt lgkmcnt(2)
	v_pk_mul_f32 v[110:111], v[0:1], v[12:13] op_sel_hi:[1,0]
	v_pk_mul_f32 v[38:39], v[28:29], v[20:21] op_sel_hi:[1,0]
	v_pk_fma_f32 v[110:111], v[2:3], v[12:13], v[110:111] op_sel:[0,1,0]
	v_pk_mul_f32 v[82:83], v[28:29], v[20:21] op_sel:[0,1]
	v_pk_fma_f32 v[110:111], v[4:5], v[14:15], v[110:111] op_sel_hi:[1,0,1]
	v_pk_mul_f32 v[116:117], v[28:29], v[22:23] op_sel_hi:[1,0]
	v_pk_fma_f32 v[110:111], v[6:7], v[14:15], v[110:111] op_sel:[0,1,0]
	v_pk_mul_f32 v[114:115], v[28:29], v[22:23] op_sel:[0,1]
	ds_read_b128 v[34:37], v69 offset:23296
	ds_read_b128 v[78:81], v69 offset:23808
	ds_read_b64 v[108:109], v118 offset:24320
	ds_read_b128 v[30:33], v69 offset:23040
	ds_read_b128 v[74:77], v69 offset:23552
	ds_read_b128 v[104:107], v69 offset:24064
	v_add_f32_dpp v110, v110, v110 row_ror:8 row_mask:0xf bank_mask:0xf bound_ctrl:1
	v_add_f32_dpp v111, v111, v111 row_ror:8 row_mask:0xf bank_mask:0xf bound_ctrl:1
	v_pk_fma_f32 v[38:39], v[0:1], v[8:9], v[38:39] op_sel_hi:[1,0,1]
	v_add_f32_dpp v110, v110, v110 row_ror:4 row_mask:0xf bank_mask:0xf bound_ctrl:1
	v_add_f32_dpp v111, v111, v111 row_ror:4 row_mask:0xf bank_mask:0xf bound_ctrl:1
	v_pk_fma_f32 v[82:83], v[2:3], v[8:9], v[82:83] op_sel:[0,1,0]
	v_add_f32_dpp v110, v110, v110 row_ror:2 row_mask:0xf bank_mask:0xf bound_ctrl:1
	v_add_f32_dpp v111, v111, v111 row_ror:2 row_mask:0xf bank_mask:0xf bound_ctrl:1
	v_pk_fma_f32 v[116:117], v[4:5], v[10:11], v[116:117] op_sel_hi:[1,0,1]
	v_add_f32_dpp v110, v110, v110 row_ror:1 row_mask:0xf bank_mask:0xf bound_ctrl:1
	v_add_f32_dpp v111, v111, v111 row_ror:1 row_mask:0xf bank_mask:0xf bound_ctrl:1
	v_pk_fma_f32 v[114:115], v[6:7], v[10:11], v[114:115] op_sel:[0,1,0]
	v_pk_fma_f32 v[0:1], v[110:111], v[16:17], v[38:39] op_sel_hi:[1,0,1]
	v_pk_fma_f32 v[2:3], v[110:111], v[16:17], v[82:83] op_sel:[0,1,0]
	v_pk_fma_f32 v[4:5], v[110:111], v[18:19], v[116:117] op_sel_hi:[1,0,1]
	v_pk_fma_f32 v[6:7], v[110:111], v[18:19], v[114:115] op_sel:[0,1,0]
	v_pk_mul_f32 v[112:113], v[0:1], v[24:25] op_sel_hi:[1,0]
	v_pk_fma_f32 v[112:113], v[2:3], v[24:25], v[112:113] op_sel:[0,1,0]
	v_pk_fma_f32 v[112:113], v[4:5], v[26:27], v[112:113] op_sel_hi:[1,0,1]
	v_pk_fma_f32 v[112:113], v[6:7], v[26:27], v[112:113] op_sel:[0,1,0]
	ds_write_b32 v119, v112 offset:28672
	ds_write_b32 v119, v113 offset:28736
	s_waitcnt lgkmcnt(2)
	v_pk_mul_f32 v[110:111], v[0:1], v[34:35] op_sel_hi:[1,0]
	v_pk_mul_f32 v[38:39], v[108:109], v[78:79] op_sel_hi:[1,0]
	v_pk_fma_f32 v[110:111], v[2:3], v[34:35], v[110:111] op_sel:[0,1,0]
	v_pk_mul_f32 v[82:83], v[108:109], v[78:79] op_sel:[0,1]
	v_pk_fma_f32 v[110:111], v[4:5], v[36:37], v[110:111] op_sel_hi:[1,0,1]
	v_pk_mul_f32 v[116:117], v[108:109], v[80:81] op_sel_hi:[1,0]
	v_pk_fma_f32 v[110:111], v[6:7], v[36:37], v[110:111] op_sel:[0,1,0]
	v_pk_mul_f32 v[114:115], v[108:109], v[80:81] op_sel:[0,1]
	s_nop 0
	v_add_f32_dpp v110, v110, v110 row_ror:8 row_mask:0xf bank_mask:0xf bound_ctrl:1
	v_add_f32_dpp v111, v111, v111 row_ror:8 row_mask:0xf bank_mask:0xf bound_ctrl:1
	v_pk_fma_f32 v[38:39], v[0:1], v[30:31], v[38:39] op_sel_hi:[1,0,1]
	v_add_f32_dpp v110, v110, v110 row_ror:4 row_mask:0xf bank_mask:0xf bound_ctrl:1
	v_add_f32_dpp v111, v111, v111 row_ror:4 row_mask:0xf bank_mask:0xf bound_ctrl:1
	v_pk_fma_f32 v[82:83], v[2:3], v[30:31], v[82:83] op_sel:[0,1,0]
	v_add_f32_dpp v110, v110, v110 row_ror:2 row_mask:0xf bank_mask:0xf bound_ctrl:1
	v_add_f32_dpp v111, v111, v111 row_ror:2 row_mask:0xf bank_mask:0xf bound_ctrl:1
	v_pk_fma_f32 v[116:117], v[4:5], v[32:33], v[116:117] op_sel_hi:[1,0,1]
	v_add_f32_dpp v110, v110, v110 row_ror:1 row_mask:0xf bank_mask:0xf bound_ctrl:1
	v_add_f32_dpp v111, v111, v111 row_ror:1 row_mask:0xf bank_mask:0xf bound_ctrl:1
	v_pk_fma_f32 v[114:115], v[6:7], v[32:33], v[114:115] op_sel:[0,1,0]
	v_pk_fma_f32 v[0:1], v[110:111], v[74:75], v[38:39] op_sel_hi:[1,0,1]
	v_pk_fma_f32 v[2:3], v[110:111], v[74:75], v[82:83] op_sel:[0,1,0]
	v_pk_fma_f32 v[4:5], v[110:111], v[76:77], v[116:117] op_sel_hi:[1,0,1]
	v_pk_fma_f32 v[6:7], v[110:111], v[76:77], v[114:115] op_sel:[0,1,0]
	v_pk_mul_f32 v[112:113], v[0:1], v[104:105] op_sel_hi:[1,0]
	v_pk_fma_f32 v[112:113], v[2:3], v[104:105], v[112:113] op_sel:[0,1,0]
	v_pk_fma_f32 v[112:113], v[4:5], v[106:107], v[112:113] op_sel_hi:[1,0,1]
	v_pk_fma_f32 v[112:113], v[6:7], v[106:107], v[112:113] op_sel:[0,1,0]
	ds_write_b32 v119, v112 offset:30720
	ds_write_b32 v119, v113 offset:30784
	s_setprio 0

.LBB0_151:
	s_andn2_saveexec_b64 s[10:11], s[12:13]
	s_cbranch_execz .LBB0_140
	v_bfe_u32 v119, v171, 4, 2
	v_lshl_add_u32 v118, v119, 2, v100
	v_lshl_add_u32 v119, v119, 6, v94
	v_add_u32_e32 v119, 0x18000, v119
	ds_read_b128 v[12:15], v69 offset:24832
	ds_read_b128 v[20:23], v69 offset:25344
	ds_read_b64 v[28:29], v118 offset:25856
	ds_read_b128 v[8:11], v69 offset:24576
	ds_read_b128 v[16:19], v69 offset:25088
	ds_read_b128 v[24:27], v69 offset:25600
	s_setprio 3
	s_waitcnt lgkmcnt(0)
	v_pk_mul_f32 v[110:111], v[0:1], v[12:13] op_sel_hi:[1,0]
	v_pk_mul_f32 v[38:39], v[28:29], v[20:21] op_sel_hi:[1,0]
	v_pk_fma_f32 v[110:111], v[2:3], v[12:13], v[110:111] op_sel:[0,1,0]
	v_pk_mul_f32 v[82:83], v[28:29], v[20:21] op_sel:[0,1]
	v_pk_fma_f32 v[110:111], v[4:5], v[14:15], v[110:111] op_sel_hi:[1,0,1]
	v_pk_mul_f32 v[116:117], v[28:29], v[22:23] op_sel_hi:[1,0]
	v_pk_fma_f32 v[110:111], v[6:7], v[14:15], v[110:111] op_sel:[0,1,0]
	v_pk_mul_f32 v[114:115], v[28:29], v[22:23] op_sel:[0,1]
	ds_read_b128 v[34:37], v69 offset:26368
	ds_read_b128 v[78:81], v69 offset:26880
	ds_read_b64 v[108:109], v118 offset:27392
	ds_read_b128 v[30:33], v69 offset:26112
	ds_read_b128 v[74:77], v69 offset:26624
	ds_read_b128 v[104:107], v69 offset:27136
	v_add_f32_dpp v110, v110, v110 row_ror:8 row_mask:0xf bank_mask:0xf bound_ctrl:1
	v_add_f32_dpp v111, v111, v111 row_ror:8 row_mask:0xf bank_mask:0xf bound_ctrl:1
	v_pk_fma_f32 v[38:39], v[0:1], v[8:9], v[38:39] op_sel_hi:[1,0,1]
	v_add_f32_dpp v110, v110, v110 row_ror:4 row_mask:0xf bank_mask:0xf bound_ctrl:1
	v_add_f32_dpp v111, v111, v111 row_ror:4 row_mask:0xf bank_mask:0xf bound_ctrl:1
	v_pk_fma_f32 v[82:83], v[2:3], v[8:9], v[82:83] op_sel:[0,1,0]
	v_add_f32_dpp v110, v110, v110 row_ror:2 row_mask:0xf bank_mask:0xf bound_ctrl:1
	v_add_f32_dpp v111, v111, v111 row_ror:2 row_mask:0xf bank_mask:0xf bound_ctrl:1
	v_pk_fma_f32 v[116:117], v[4:5], v[10:11], v[116:117] op_sel_hi:[1,0,1]
	v_add_f32_dpp v110, v110, v110 row_ror:1 row_mask:0xf bank_mask:0xf bound_ctrl:1
	v_add_f32_dpp v111, v111, v111 row_ror:1 row_mask:0xf bank_mask:0xf bound_ctrl:1
	v_pk_fma_f32 v[114:115], v[6:7], v[10:11], v[114:115] op_sel:[0,1,0]
	v_pk_fma_f32 v[0:1], v[110:111], v[16:17], v[38:39] op_sel_hi:[1,0,1]
	v_pk_fma_f32 v[2:3], v[110:111], v[16:17], v[82:83] op_sel:[0,1,0]
	v_pk_fma_f32 v[4:5], v[110:111], v[18:19], v[116:117] op_sel_hi:[1,0,1]
	v_pk_fma_f32 v[6:7], v[110:111], v[18:19], v[114:115] op_sel:[0,1,0]
	v_pk_mul_f32 v[112:113], v[0:1], v[24:25] op_sel_hi:[1,0]
	v_pk_fma_f32 v[112:113], v[2:3], v[24:25], v[112:113] op_sel:[0,1,0]
	v_pk_fma_f32 v[112:113], v[4:5], v[26:27], v[112:113] op_sel_hi:[1,0,1]
	v_pk_fma_f32 v[112:113], v[6:7], v[26:27], v[112:113] op_sel:[0,1,0]
	ds_write_b32 v119, v112 offset:0
	ds_write_b32 v119, v113 offset:64
	s_waitcnt lgkmcnt(2)
	v_pk_mul_f32 v[110:111], v[0:1], v[34:35] op_sel_hi:[1,0]
	v_pk_mul_f32 v[38:39], v[108:109], v[78:79] op_sel_hi:[1,0]
	v_pk_fma_f32 v[110:111], v[2:3], v[34:35], v[110:111] op_sel:[0,1,0]
	v_pk_mul_f32 v[82:83], v[108:109], v[78:79] op_sel:[0,1]
	v_pk_fma_f32 v[110:111], v[4:5], v[36:37], v[110:111] op_sel_hi:[1,0,1]
	v_pk_mul_f32 v[116:117], v[108:109], v[80:81] op_sel_hi:[1,0]
	v_pk_fma_f32 v[110:111], v[6:7], v[36:37], v[110:111] op_sel:[0,1,0]
	v_pk_mul_f32 v[114:115], v[108:109], v[80:81] op_sel:[0,1]
	ds_read_b128 v[12:15], v69 offset:27904
	ds_read_b128 v[20:23], v69 offset:28416
	ds_read_b64 v[28:29], v118 offset:28928
	ds_read_b128 v[8:11], v69 offset:27648
	ds_read_b128 v[16:19], v69 offset:28160
	ds_read_b128 v[24:27], v69 offset:28672
	v_add_f32_dpp v110, v110, v110 row_ror:8 row_mask:0xf bank_mask:0xf bound_ctrl:1
	v_add_f32_dpp v111, v111, v111 row_ror:8 row_mask:0xf bank_mask:0xf bound_ctrl:1
	v_pk_fma_f32 v[38:39], v[0:1], v[30:31], v[38:39] op_sel_hi:[1,0,1]
	v_add_f32_dpp v110, v110, v110 row_ror:4 row_mask:0xf bank_mask:0xf bound_ctrl:1
	v_add_f32_dpp v111, v111, v111 row_ror:4 row_mask:0xf bank_mask:0xf bound_ctrl:1
	v_pk_fma_f32 v[82:83], v[2:3], v[30:31], v[82:83] op_sel:[0,1,0]
	v_add_f32_dpp v110, v110, v110 row_ror:2 row_mask:0xf bank_mask:0xf bound_ctrl:1
	v_add_f32_dpp v111, v111, v111 row_ror:2 row_mask:0xf bank_mask:0xf bound_ctrl:1
	v_pk_fma_f32 v[116:117], v[4:5], v[32:33], v[116:117] op_sel_hi:[1,0,1]
	v_add_f32_dpp v110, v110, v110 row_ror:1 row_mask:0xf bank_mask:0xf bound_ctrl:1
	v_add_f32_dpp v111, v111, v111 row_ror:1 row_mask:0xf bank_mask:0xf bound_ctrl:1
	v_pk_fma_f32 v[114:115], v[6:7], v[32:33], v[114:115] op_sel:[0,1,0]
	v_pk_fma_f32 v[0:1], v[110:111], v[74:75], v[38:39] op_sel_hi:[1,0,1]
	v_pk_fma_f32 v[2:3], v[110:111], v[74:75], v[82:83] op_sel:[0,1,0]
	v_pk_fma_f32 v[4:5], v[110:111], v[76:77], v[116:117] op_sel_hi:[1,0,1]
	v_pk_fma_f32 v[6:7], v[110:111], v[76:77], v[114:115] op_sel:[0,1,0]
	v_pk_mul_f32 v[112:113], v[0:1], v[104:105] op_sel_hi:[1,0]
	v_pk_fma_f32 v[112:113], v[2:3], v[104:105], v[112:113] op_sel:[0,1,0]
	v_pk_fma_f32 v[112:113], v[4:5], v[106:107], v[112:113] op_sel_hi:[1,0,1]
	v_pk_fma_f32 v[112:113], v[6:7], v[106:107], v[112:113] op_sel:[0,1,0]
	ds_write_b32 v119, v112 offset:2048
	ds_write_b32 v119, v113 offset:2112
	s_waitcnt lgkmcnt(2)
	v_pk_mul_f32 v[110:111], v[0:1], v[12:13] op_sel_hi:[1,0]
	v_pk_mul_f32 v[38:39], v[28:29], v[20:21] op_sel_hi:[1,0]
	v_pk_fma_f32 v[110:111], v[2:3], v[12:13], v[110:111] op_sel:[0,1,0]
	v_pk_mul_f32 v[82:83], v[28:29], v[20:21] op_sel:[0,1]
	v_pk_fma_f32 v[110:111], v[4:5], v[14:15], v[110:111] op_sel_hi:[1,0,1]
	v_pk_mul_f32 v[116:117], v[28:29], v[22:23] op_sel_hi:[1,0]
	v_pk_fma_f32 v[110:111], v[6:7], v[14:15], v[110:111] op_sel:[0,1,0]
	v_pk_mul_f32 v[114:115], v[28:29], v[22:23] op_sel:[0,1]
	ds_read_b128 v[34:37], v69 offset:29440
	ds_read_b128 v[78:81], v69 offset:29952
	ds_read_b64 v[108:109], v118 offset:30464
	ds_read_b128 v[30:33], v69 offset:29184
	ds_read_b128 v[74:77], v69 offset:29696
	ds_read_b128 v[104:107], v69 offset:30208
	v_add_f32_dpp v110, v110, v110 row_ror:8 row_mask:0xf bank_mask:0xf bound_ctrl:1
	v_add_f32_dpp v111, v111, v111 row_ror:8 row_mask:0xf bank_mask:0xf bound_ctrl:1
	v_pk_fma_f32 v[38:39], v[0:1], v[8:9], v[38:39] op_sel_hi:[1,0,1]
	v_add_f32_dpp v110, v110, v110 row_ror:4 row_mask:0xf bank_mask:0xf bound_ctrl:1
	v_add_f32_dpp v111, v111, v111 row_ror:4 row_mask:0xf bank_mask:0xf bound_ctrl:1
	v_pk_fma_f32 v[82:83], v[2:3], v[8:9], v[82:83] op_sel:[0,1,0]
	v_add_f32_dpp v110, v110, v110 row_ror:2 row_mask:0xf bank_mask:0xf bound_ctrl:1
	v_add_f32_dpp v111, v111, v111 row_ror:2 row_mask:0xf bank_mask:0xf bound_ctrl:1
	v_pk_fma_f32 v[116:117], v[4:5], v[10:11], v[116:117] op_sel_hi:[1,0,1]
	v_add_f32_dpp v110, v110, v110 row_ror:1 row_mask:0xf bank_mask:0xf bound_ctrl:1
	v_add_f32_dpp v111, v111, v111 row_ror:1 row_mask:0xf bank_mask:0xf bound_ctrl:1
	v_pk_fma_f32 v[114:115], v[6:7], v[10:11], v[114:115] op_sel:[0,1,0]
	v_pk_fma_f32 v[0:1], v[110:111], v[16:17], v[38:39] op_sel_hi:[1,0,1]
	v_pk_fma_f32 v[2:3], v[110:111], v[16:17], v[82:83] op_sel:[0,1,0]
	v_pk_fma_f32 v[4:5], v[110:111], v[18:19], v[116:117] op_sel_hi:[1,0,1]
	v_pk_fma_f32 v[6:7], v[110:111], v[18:19], v[114:115] op_sel:[0,1,0]
	v_pk_mul_f32 v[112:113], v[0:1], v[24:25] op_sel_hi:[1,0]
	v_pk_fma_f32 v[112:113], v[2:3], v[24:25], v[112:113] op_sel:[0,1,0]
	v_pk_fma_f32 v[112:113], v[4:5], v[26:27], v[112:113] op_sel_hi:[1,0,1]
	v_pk_fma_f32 v[112:113], v[6:7], v[26:27], v[112:113] op_sel:[0,1,0]
	ds_write_b32 v119, v112 offset:4096
	ds_write_b32 v119, v113 offset:4160
	s_waitcnt lgkmcnt(2)
	v_pk_mul_f32 v[110:111], v[0:1], v[34:35] op_sel_hi:[1,0]
	v_pk_mul_f32 v[38:39], v[108:109], v[78:79] op_sel_hi:[1,0]
	v_pk_fma_f32 v[110:111], v[2:3], v[34:35], v[110:111] op_sel:[0,1,0]
	v_pk_mul_f32 v[82:83], v[108:109], v[78:79] op_sel:[0,1]
	v_pk_fma_f32 v[110:111], v[4:5], v[36:37], v[110:111] op_sel_hi:[1,0,1]
	v_pk_mul_f32 v[116:117], v[108:109], v[80:81] op_sel_hi:[1,0]
	v_pk_fma_f32 v[110:111], v[6:7], v[36:37], v[110:111] op_sel:[0,1,0]
	v_pk_mul_f32 v[114:115], v[108:109], v[80:81] op_sel:[0,1]
	ds_read_b128 v[12:15], v69 offset:30976
	ds_read_b128 v[20:23], v69 offset:31488
	ds_read_b64 v[28:29], v118 offset:32000
	ds_read_b128 v[8:11], v69 offset:30720
	ds_read_b128 v[16:19], v69 offset:31232
	ds_read_b128 v[24:27], v69 offset:31744
	v_add_f32_dpp v110, v110, v110 row_ror:8 row_mask:0xf bank_mask:0xf bound_ctrl:1
	v_add_f32_dpp v111, v111, v111 row_ror:8 row_mask:0xf bank_mask:0xf bound_ctrl:1
	v_pk_fma_f32 v[38:39], v[0:1], v[30:31], v[38:39] op_sel_hi:[1,0,1]
	v_add_f32_dpp v110, v110, v110 row_ror:4 row_mask:0xf bank_mask:0xf bound_ctrl:1
	v_add_f32_dpp v111, v111, v111 row_ror:4 row_mask:0xf bank_mask:0xf bound_ctrl:1
	v_pk_fma_f32 v[82:83], v[2:3], v[30:31], v[82:83] op_sel:[0,1,0]
	v_add_f32_dpp v110, v110, v110 row_ror:2 row_mask:0xf bank_mask:0xf bound_ctrl:1
	v_add_f32_dpp v111, v111, v111 row_ror:2 row_mask:0xf bank_mask:0xf bound_ctrl:1
	v_pk_fma_f32 v[116:117], v[4:5], v[32:33], v[116:117] op_sel_hi:[1,0,1]
	v_add_f32_dpp v110, v110, v110 row_ror:1 row_mask:0xf bank_mask:0xf bound_ctrl:1
	v_add_f32_dpp v111, v111, v111 row_ror:1 row_mask:0xf bank_mask:0xf bound_ctrl:1
	v_pk_fma_f32 v[114:115], v[6:7], v[32:33], v[114:115] op_sel:[0,1,0]
	v_pk_fma_f32 v[0:1], v[110:111], v[74:75], v[38:39] op_sel_hi:[1,0,1]
	v_pk_fma_f32 v[2:3], v[110:111], v[74:75], v[82:83] op_sel:[0,1,0]
	v_pk_fma_f32 v[4:5], v[110:111], v[76:77], v[116:117] op_sel_hi:[1,0,1]
	v_pk_fma_f32 v[6:7], v[110:111], v[76:77], v[114:115] op_sel:[0,1,0]
	v_pk_mul_f32 v[112:113], v[0:1], v[104:105] op_sel_hi:[1,0]
	v_pk_fma_f32 v[112:113], v[2:3], v[104:105], v[112:113] op_sel:[0,1,0]
	v_pk_fma_f32 v[112:113], v[4:5], v[106:107], v[112:113] op_sel_hi:[1,0,1]
	v_pk_fma_f32 v[112:113], v[6:7], v[106:107], v[112:113] op_sel:[0,1,0]
	ds_write_b32 v119, v112 offset:6144
	ds_write_b32 v119, v113 offset:6208
	s_waitcnt lgkmcnt(2)
	v_pk_mul_f32 v[110:111], v[0:1], v[12:13] op_sel_hi:[1,0]
	v_pk_mul_f32 v[38:39], v[28:29], v[20:21] op_sel_hi:[1,0]
	v_pk_fma_f32 v[110:111], v[2:3], v[12:13], v[110:111] op_sel:[0,1,0]
	v_pk_mul_f32 v[82:83], v[28:29], v[20:21] op_sel:[0,1]
	v_pk_fma_f32 v[110:111], v[4:5], v[14:15], v[110:111] op_sel_hi:[1,0,1]
	v_pk_mul_f32 v[116:117], v[28:29], v[22:23] op_sel_hi:[1,0]
	v_pk_fma_f32 v[110:111], v[6:7], v[14:15], v[110:111] op_sel:[0,1,0]
	v_pk_mul_f32 v[114:115], v[28:29], v[22:23] op_sel:[0,1]
	ds_read_b128 v[34:37], v69 offset:32512
	ds_read_b128 v[78:81], v69 offset:33024
	ds_read_b64 v[108:109], v118 offset:33536
	ds_read_b128 v[30:33], v69 offset:32256
	ds_read_b128 v[74:77], v69 offset:32768
	ds_read_b128 v[104:107], v69 offset:33280
	v_add_f32_dpp v110, v110, v110 row_ror:8 row_mask:0xf bank_mask:0xf bound_ctrl:1
	v_add_f32_dpp v111, v111, v111 row_ror:8 row_mask:0xf bank_mask:0xf bound_ctrl:1
	v_pk_fma_f32 v[38:39], v[0:1], v[8:9], v[38:39] op_sel_hi:[1,0,1]
	v_add_f32_dpp v110, v110, v110 row_ror:4 row_mask:0xf bank_mask:0xf bound_ctrl:1
	v_add_f32_dpp v111, v111, v111 row_ror:4 row_mask:0xf bank_mask:0xf bound_ctrl:1
	v_pk_fma_f32 v[82:83], v[2:3], v[8:9], v[82:83] op_sel:[0,1,0]
	v_add_f32_dpp v110, v110, v110 row_ror:2 row_mask:0xf bank_mask:0xf bound_ctrl:1
	v_add_f32_dpp v111, v111, v111 row_ror:2 row_mask:0xf bank_mask:0xf bound_ctrl:1
	v_pk_fma_f32 v[116:117], v[4:5], v[10:11], v[116:117] op_sel_hi:[1,0,1]
	v_add_f32_dpp v110, v110, v110 row_ror:1 row_mask:0xf bank_mask:0xf bound_ctrl:1
	v_add_f32_dpp v111, v111, v111 row_ror:1 row_mask:0xf bank_mask:0xf bound_ctrl:1
	v_pk_fma_f32 v[114:115], v[6:7], v[10:11], v[114:115] op_sel:[0,1,0]
	v_pk_fma_f32 v[0:1], v[110:111], v[16:17], v[38:39] op_sel_hi:[1,0,1]
	v_pk_fma_f32 v[2:3], v[110:111], v[16:17], v[82:83] op_sel:[0,1,0]
	v_pk_fma_f32 v[4:5], v[110:111], v[18:19], v[116:117] op_sel_hi:[1,0,1]
	v_pk_fma_f32 v[6:7], v[110:111], v[18:19], v[114:115] op_sel:[0,1,0]
	v_pk_mul_f32 v[112:113], v[0:1], v[24:25] op_sel_hi:[1,0]
	v_pk_fma_f32 v[112:113], v[2:3], v[24:25], v[112:113] op_sel:[0,1,0]
	v_pk_fma_f32 v[112:113], v[4:5], v[26:27], v[112:113] op_sel_hi:[1,0,1]
	v_pk_fma_f32 v[112:113], v[6:7], v[26:27], v[112:113] op_sel:[0,1,0]
	ds_write_b32 v119, v112 offset:8192
	ds_write_b32 v119, v113 offset:8256
	s_waitcnt lgkmcnt(2)
	v_pk_mul_f32 v[110:111], v[0:1], v[34:35] op_sel_hi:[1,0]
	v_pk_mul_f32 v[38:39], v[108:109], v[78:79] op_sel_hi:[1,0]
	v_pk_fma_f32 v[110:111], v[2:3], v[34:35], v[110:111] op_sel:[0,1,0]
	v_pk_mul_f32 v[82:83], v[108:109], v[78:79] op_sel:[0,1]
	v_pk_fma_f32 v[110:111], v[4:5], v[36:37], v[110:111] op_sel_hi:[1,0,1]
	v_pk_mul_f32 v[116:117], v[108:109], v[80:81] op_sel_hi:[1,0]
	v_pk_fma_f32 v[110:111], v[6:7], v[36:37], v[110:111] op_sel:[0,1,0]
	v_pk_mul_f32 v[114:115], v[108:109], v[80:81] op_sel:[0,1]
	ds_read_b128 v[12:15], v69 offset:34048
	ds_read_b128 v[20:23], v69 offset:34560
	ds_read_b64 v[28:29], v118 offset:35072
	ds_read_b128 v[8:11], v69 offset:33792
	ds_read_b128 v[16:19], v69 offset:34304
	ds_read_b128 v[24:27], v69 offset:34816
	v_add_f32_dpp v110, v110, v110 row_ror:8 row_mask:0xf bank_mask:0xf bound_ctrl:1
	v_add_f32_dpp v111, v111, v111 row_ror:8 row_mask:0xf bank_mask:0xf bound_ctrl:1
	v_pk_fma_f32 v[38:39], v[0:1], v[30:31], v[38:39] op_sel_hi:[1,0,1]
	v_add_f32_dpp v110, v110, v110 row_ror:4 row_mask:0xf bank_mask:0xf bound_ctrl:1
	v_add_f32_dpp v111, v111, v111 row_ror:4 row_mask:0xf bank_mask:0xf bound_ctrl:1
	v_pk_fma_f32 v[82:83], v[2:3], v[30:31], v[82:83] op_sel:[0,1,0]
	v_add_f32_dpp v110, v110, v110 row_ror:2 row_mask:0xf bank_mask:0xf bound_ctrl:1
	v_add_f32_dpp v111, v111, v111 row_ror:2 row_mask:0xf bank_mask:0xf bound_ctrl:1
	v_pk_fma_f32 v[116:117], v[4:5], v[32:33], v[116:117] op_sel_hi:[1,0,1]
	v_add_f32_dpp v110, v110, v110 row_ror:1 row_mask:0xf bank_mask:0xf bound_ctrl:1
	v_add_f32_dpp v111, v111, v111 row_ror:1 row_mask:0xf bank_mask:0xf bound_ctrl:1
	v_pk_fma_f32 v[114:115], v[6:7], v[32:33], v[114:115] op_sel:[0,1,0]
	v_pk_fma_f32 v[0:1], v[110:111], v[74:75], v[38:39] op_sel_hi:[1,0,1]
	v_pk_fma_f32 v[2:3], v[110:111], v[74:75], v[82:83] op_sel:[0,1,0]
	v_pk_fma_f32 v[4:5], v[110:111], v[76:77], v[116:117] op_sel_hi:[1,0,1]
	v_pk_fma_f32 v[6:7], v[110:111], v[76:77], v[114:115] op_sel:[0,1,0]
	v_pk_mul_f32 v[112:113], v[0:1], v[104:105] op_sel_hi:[1,0]
	v_pk_fma_f32 v[112:113], v[2:3], v[104:105], v[112:113] op_sel:[0,1,0]
	v_pk_fma_f32 v[112:113], v[4:5], v[106:107], v[112:113] op_sel_hi:[1,0,1]
	v_pk_fma_f32 v[112:113], v[6:7], v[106:107], v[112:113] op_sel:[0,1,0]
	ds_write_b32 v119, v112 offset:10240
	ds_write_b32 v119, v113 offset:10304
	s_waitcnt lgkmcnt(2)
	v_pk_mul_f32 v[110:111], v[0:1], v[12:13] op_sel_hi:[1,0]
	v_pk_mul_f32 v[38:39], v[28:29], v[20:21] op_sel_hi:[1,0]
	v_pk_fma_f32 v[110:111], v[2:3], v[12:13], v[110:111] op_sel:[0,1,0]
	v_pk_mul_f32 v[82:83], v[28:29], v[20:21] op_sel:[0,1]
	v_pk_fma_f32 v[110:111], v[4:5], v[14:15], v[110:111] op_sel_hi:[1,0,1]
	v_pk_mul_f32 v[116:117], v[28:29], v[22:23] op_sel_hi:[1,0]
	v_pk_fma_f32 v[110:111], v[6:7], v[14:15], v[110:111] op_sel:[0,1,0]
	v_pk_mul_f32 v[114:115], v[28:29], v[22:23] op_sel:[0,1]
	ds_read_b128 v[34:37], v69 offset:35584
	ds_read_b128 v[78:81], v69 offset:36096
	ds_read_b64 v[108:109], v118 offset:36608
	ds_read_b128 v[30:33], v69 offset:35328
	ds_read_b128 v[74:77], v69 offset:35840
	ds_read_b128 v[104:107], v69 offset:36352
	v_add_f32_dpp v110, v110, v110 row_ror:8 row_mask:0xf bank_mask:0xf bound_ctrl:1
	v_add_f32_dpp v111, v111, v111 row_ror:8 row_mask:0xf bank_mask:0xf bound_ctrl:1
	v_pk_fma_f32 v[38:39], v[0:1], v[8:9], v[38:39] op_sel_hi:[1,0,1]
	v_add_f32_dpp v110, v110, v110 row_ror:4 row_mask:0xf bank_mask:0xf bound_ctrl:1
	v_add_f32_dpp v111, v111, v111 row_ror:4 row_mask:0xf bank_mask:0xf bound_ctrl:1
	v_pk_fma_f32 v[82:83], v[2:3], v[8:9], v[82:83] op_sel:[0,1,0]
	v_add_f32_dpp v110, v110, v110 row_ror:2 row_mask:0xf bank_mask:0xf bound_ctrl:1
	v_add_f32_dpp v111, v111, v111 row_ror:2 row_mask:0xf bank_mask:0xf bound_ctrl:1
	v_pk_fma_f32 v[116:117], v[4:5], v[10:11], v[116:117] op_sel_hi:[1,0,1]
	v_add_f32_dpp v110, v110, v110 row_ror:1 row_mask:0xf bank_mask:0xf bound_ctrl:1
	v_add_f32_dpp v111, v111, v111 row_ror:1 row_mask:0xf bank_mask:0xf bound_ctrl:1
	v_pk_fma_f32 v[114:115], v[6:7], v[10:11], v[114:115] op_sel:[0,1,0]
	v_pk_fma_f32 v[0:1], v[110:111], v[16:17], v[38:39] op_sel_hi:[1,0,1]
	v_pk_fma_f32 v[2:3], v[110:111], v[16:17], v[82:83] op_sel:[0,1,0]
	v_pk_fma_f32 v[4:5], v[110:111], v[18:19], v[116:117] op_sel_hi:[1,0,1]
	v_pk_fma_f32 v[6:7], v[110:111], v[18:19], v[114:115] op_sel:[0,1,0]
	v_pk_mul_f32 v[112:113], v[0:1], v[24:25] op_sel_hi:[1,0]
	v_pk_fma_f32 v[112:113], v[2:3], v[24:25], v[112:113] op_sel:[0,1,0]
	v_pk_fma_f32 v[112:113], v[4:5], v[26:27], v[112:113] op_sel_hi:[1,0,1]
	v_pk_fma_f32 v[112:113], v[6:7], v[26:27], v[112:113] op_sel:[0,1,0]
	ds_write_b32 v119, v112 offset:12288
	ds_write_b32 v119, v113 offset:12352
	s_waitcnt lgkmcnt(2)
	v_pk_mul_f32 v[110:111], v[0:1], v[34:35] op_sel_hi:[1,0]
	v_pk_mul_f32 v[38:39], v[108:109], v[78:79] op_sel_hi:[1,0]
	v_pk_fma_f32 v[110:111], v[2:3], v[34:35], v[110:111] op_sel:[0,1,0]
	v_pk_mul_f32 v[82:83], v[108:109], v[78:79] op_sel:[0,1]
	v_pk_fma_f32 v[110:111], v[4:5], v[36:37], v[110:111] op_sel_hi:[1,0,1]
	v_pk_mul_f32 v[116:117], v[108:109], v[80:81] op_sel_hi:[1,0]
	v_pk_fma_f32 v[110:111], v[6:7], v[36:37], v[110:111] op_sel:[0,1,0]
	v_pk_mul_f32 v[114:115], v[108:109], v[80:81] op_sel:[0,1]
	ds_read_b128 v[12:15], v69 offset:37120
	ds_read_b128 v[20:23], v69 offset:37632
	ds_read_b64 v[28:29], v118 offset:38144
	ds_read_b128 v[8:11], v69 offset:36864
	ds_read_b128 v[16:19], v69 offset:37376
	ds_read_b128 v[24:27], v69 offset:37888
	v_add_f32_dpp v110, v110, v110 row_ror:8 row_mask:0xf bank_mask:0xf bound_ctrl:1
	v_add_f32_dpp v111, v111, v111 row_ror:8 row_mask:0xf bank_mask:0xf bound_ctrl:1
	v_pk_fma_f32 v[38:39], v[0:1], v[30:31], v[38:39] op_sel_hi:[1,0,1]
	v_add_f32_dpp v110, v110, v110 row_ror:4 row_mask:0xf bank_mask:0xf bound_ctrl:1
	v_add_f32_dpp v111, v111, v111 row_ror:4 row_mask:0xf bank_mask:0xf bound_ctrl:1
	v_pk_fma_f32 v[82:83], v[2:3], v[30:31], v[82:83] op_sel:[0,1,0]
	v_add_f32_dpp v110, v110, v110 row_ror:2 row_mask:0xf bank_mask:0xf bound_ctrl:1
	v_add_f32_dpp v111, v111, v111 row_ror:2 row_mask:0xf bank_mask:0xf bound_ctrl:1
	v_pk_fma_f32 v[116:117], v[4:5], v[32:33], v[116:117] op_sel_hi:[1,0,1]
	v_add_f32_dpp v110, v110, v110 row_ror:1 row_mask:0xf bank_mask:0xf bound_ctrl:1
	v_add_f32_dpp v111, v111, v111 row_ror:1 row_mask:0xf bank_mask:0xf bound_ctrl:1
	v_pk_fma_f32 v[114:115], v[6:7], v[32:33], v[114:115] op_sel:[0,1,0]
	v_pk_fma_f32 v[0:1], v[110:111], v[74:75], v[38:39] op_sel_hi:[1,0,1]
	v_pk_fma_f32 v[2:3], v[110:111], v[74:75], v[82:83] op_sel:[0,1,0]
	v_pk_fma_f32 v[4:5], v[110:111], v[76:77], v[116:117] op_sel_hi:[1,0,1]
	v_pk_fma_f32 v[6:7], v[110:111], v[76:77], v[114:115] op_sel:[0,1,0]
	v_pk_mul_f32 v[112:113], v[0:1], v[104:105] op_sel_hi:[1,0]
	v_pk_fma_f32 v[112:113], v[2:3], v[104:105], v[112:113] op_sel:[0,1,0]
	v_pk_fma_f32 v[112:113], v[4:5], v[106:107], v[112:113] op_sel_hi:[1,0,1]
	v_pk_fma_f32 v[112:113], v[6:7], v[106:107], v[112:113] op_sel:[0,1,0]
	ds_write_b32 v119, v112 offset:14336
	ds_write_b32 v119, v113 offset:14400
	s_waitcnt lgkmcnt(2)
	v_pk_mul_f32 v[110:111], v[0:1], v[12:13] op_sel_hi:[1,0]
	v_pk_mul_f32 v[38:39], v[28:29], v[20:21] op_sel_hi:[1,0]
	v_pk_fma_f32 v[110:111], v[2:3], v[12:13], v[110:111] op_sel:[0,1,0]
	v_pk_mul_f32 v[82:83], v[28:29], v[20:21] op_sel:[0,1]
	v_pk_fma_f32 v[110:111], v[4:5], v[14:15], v[110:111] op_sel_hi:[1,0,1]
	v_pk_mul_f32 v[116:117], v[28:29], v[22:23] op_sel_hi:[1,0]
	v_pk_fma_f32 v[110:111], v[6:7], v[14:15], v[110:111] op_sel:[0,1,0]
	v_pk_mul_f32 v[114:115], v[28:29], v[22:23] op_sel:[0,1]
	ds_read_b128 v[34:37], v69 offset:38656
	ds_read_b128 v[78:81], v69 offset:39168
	ds_read_b64 v[108:109], v118 offset:39680
	ds_read_b128 v[30:33], v69 offset:38400
	ds_read_b128 v[74:77], v69 offset:38912
	ds_read_b128 v[104:107], v69 offset:39424
	v_add_f32_dpp v110, v110, v110 row_ror:8 row_mask:0xf bank_mask:0xf bound_ctrl:1
	v_add_f32_dpp v111, v111, v111 row_ror:8 row_mask:0xf bank_mask:0xf bound_ctrl:1
	v_pk_fma_f32 v[38:39], v[0:1], v[8:9], v[38:39] op_sel_hi:[1,0,1]
	v_add_f32_dpp v110, v110, v110 row_ror:4 row_mask:0xf bank_mask:0xf bound_ctrl:1
	v_add_f32_dpp v111, v111, v111 row_ror:4 row_mask:0xf bank_mask:0xf bound_ctrl:1
	v_pk_fma_f32 v[82:83], v[2:3], v[8:9], v[82:83] op_sel:[0,1,0]
	v_add_f32_dpp v110, v110, v110 row_ror:2 row_mask:0xf bank_mask:0xf bound_ctrl:1
	v_add_f32_dpp v111, v111, v111 row_ror:2 row_mask:0xf bank_mask:0xf bound_ctrl:1
	v_pk_fma_f32 v[116:117], v[4:5], v[10:11], v[116:117] op_sel_hi:[1,0,1]
	v_add_f32_dpp v110, v110, v110 row_ror:1 row_mask:0xf bank_mask:0xf bound_ctrl:1
	v_add_f32_dpp v111, v111, v111 row_ror:1 row_mask:0xf bank_mask:0xf bound_ctrl:1
	v_pk_fma_f32 v[114:115], v[6:7], v[10:11], v[114:115] op_sel:[0,1,0]
	v_pk_fma_f32 v[0:1], v[110:111], v[16:17], v[38:39] op_sel_hi:[1,0,1]
	v_pk_fma_f32 v[2:3], v[110:111], v[16:17], v[82:83] op_sel:[0,1,0]
	v_pk_fma_f32 v[4:5], v[110:111], v[18:19], v[116:117] op_sel_hi:[1,0,1]
	v_pk_fma_f32 v[6:7], v[110:111], v[18:19], v[114:115] op_sel:[0,1,0]
	v_pk_mul_f32 v[112:113], v[0:1], v[24:25] op_sel_hi:[1,0]
	v_pk_fma_f32 v[112:113], v[2:3], v[24:25], v[112:113] op_sel:[0,1,0]
	v_pk_fma_f32 v[112:113], v[4:5], v[26:27], v[112:113] op_sel_hi:[1,0,1]
	v_pk_fma_f32 v[112:113], v[6:7], v[26:27], v[112:113] op_sel:[0,1,0]
	ds_write_b32 v119, v112 offset:16384
	ds_write_b32 v119, v113 offset:16448
	s_waitcnt lgkmcnt(2)
	v_pk_mul_f32 v[110:111], v[0:1], v[34:35] op_sel_hi:[1,0]
	v_pk_mul_f32 v[38:39], v[108:109], v[78:79] op_sel_hi:[1,0]
	v_pk_fma_f32 v[110:111], v[2:3], v[34:35], v[110:111] op_sel:[0,1,0]
	v_pk_mul_f32 v[82:83], v[108:109], v[78:79] op_sel:[0,1]
	v_pk_fma_f32 v[110:111], v[4:5], v[36:37], v[110:111] op_sel_hi:[1,0,1]
	v_pk_mul_f32 v[116:117], v[108:109], v[80:81] op_sel_hi:[1,0]
	v_pk_fma_f32 v[110:111], v[6:7], v[36:37], v[110:111] op_sel:[0,1,0]
	v_pk_mul_f32 v[114:115], v[108:109], v[80:81] op_sel:[0,1]
	ds_read_b128 v[12:15], v69 offset:40192
	ds_read_b128 v[20:23], v69 offset:40704
	ds_read_b64 v[28:29], v118 offset:41216
	ds_read_b128 v[8:11], v69 offset:39936
	ds_read_b128 v[16:19], v69 offset:40448
	ds_read_b128 v[24:27], v69 offset:40960
	v_add_f32_dpp v110, v110, v110 row_ror:8 row_mask:0xf bank_mask:0xf bound_ctrl:1
	v_add_f32_dpp v111, v111, v111 row_ror:8 row_mask:0xf bank_mask:0xf bound_ctrl:1
	v_pk_fma_f32 v[38:39], v[0:1], v[30:31], v[38:39] op_sel_hi:[1,0,1]
	v_add_f32_dpp v110, v110, v110 row_ror:4 row_mask:0xf bank_mask:0xf bound_ctrl:1
	v_add_f32_dpp v111, v111, v111 row_ror:4 row_mask:0xf bank_mask:0xf bound_ctrl:1
	v_pk_fma_f32 v[82:83], v[2:3], v[30:31], v[82:83] op_sel:[0,1,0]
	v_add_f32_dpp v110, v110, v110 row_ror:2 row_mask:0xf bank_mask:0xf bound_ctrl:1
	v_add_f32_dpp v111, v111, v111 row_ror:2 row_mask:0xf bank_mask:0xf bound_ctrl:1
	v_pk_fma_f32 v[116:117], v[4:5], v[32:33], v[116:117] op_sel_hi:[1,0,1]
	v_add_f32_dpp v110, v110, v110 row_ror:1 row_mask:0xf bank_mask:0xf bound_ctrl:1
	v_add_f32_dpp v111, v111, v111 row_ror:1 row_mask:0xf bank_mask:0xf bound_ctrl:1
	v_pk_fma_f32 v[114:115], v[6:7], v[32:33], v[114:115] op_sel:[0,1,0]
	v_pk_fma_f32 v[0:1], v[110:111], v[74:75], v[38:39] op_sel_hi:[1,0,1]
	v_pk_fma_f32 v[2:3], v[110:111], v[74:75], v[82:83] op_sel:[0,1,0]
	v_pk_fma_f32 v[4:5], v[110:111], v[76:77], v[116:117] op_sel_hi:[1,0,1]
	v_pk_fma_f32 v[6:7], v[110:111], v[76:77], v[114:115] op_sel:[0,1,0]
	v_pk_mul_f32 v[112:113], v[0:1], v[104:105] op_sel_hi:[1,0]
	v_pk_fma_f32 v[112:113], v[2:3], v[104:105], v[112:113] op_sel:[0,1,0]
	v_pk_fma_f32 v[112:113], v[4:5], v[106:107], v[112:113] op_sel_hi:[1,0,1]
	v_pk_fma_f32 v[112:113], v[6:7], v[106:107], v[112:113] op_sel:[0,1,0]
	ds_write_b32 v119, v112 offset:18432
	ds_write_b32 v119, v113 offset:18496
	s_waitcnt lgkmcnt(2)
	v_pk_mul_f32 v[110:111], v[0:1], v[12:13] op_sel_hi:[1,0]
	v_pk_mul_f32 v[38:39], v[28:29], v[20:21] op_sel_hi:[1,0]
	v_pk_fma_f32 v[110:111], v[2:3], v[12:13], v[110:111] op_sel:[0,1,0]
	v_pk_mul_f32 v[82:83], v[28:29], v[20:21] op_sel:[0,1]
	v_pk_fma_f32 v[110:111], v[4:5], v[14:15], v[110:111] op_sel_hi:[1,0,1]
	v_pk_mul_f32 v[116:117], v[28:29], v[22:23] op_sel_hi:[1,0]
	v_pk_fma_f32 v[110:111], v[6:7], v[14:15], v[110:111] op_sel:[0,1,0]
	v_pk_mul_f32 v[114:115], v[28:29], v[22:23] op_sel:[0,1]
	ds_read_b128 v[34:37], v69 offset:41728
	ds_read_b128 v[78:81], v69 offset:42240
	ds_read_b64 v[108:109], v118 offset:42752
	ds_read_b128 v[30:33], v69 offset:41472
	ds_read_b128 v[74:77], v69 offset:41984
	ds_read_b128 v[104:107], v69 offset:42496
	v_add_f32_dpp v110, v110, v110 row_ror:8 row_mask:0xf bank_mask:0xf bound_ctrl:1
	v_add_f32_dpp v111, v111, v111 row_ror:8 row_mask:0xf bank_mask:0xf bound_ctrl:1
	v_pk_fma_f32 v[38:39], v[0:1], v[8:9], v[38:39] op_sel_hi:[1,0,1]
	v_add_f32_dpp v110, v110, v110 row_ror:4 row_mask:0xf bank_mask:0xf bound_ctrl:1
	v_add_f32_dpp v111, v111, v111 row_ror:4 row_mask:0xf bank_mask:0xf bound_ctrl:1
	v_pk_fma_f32 v[82:83], v[2:3], v[8:9], v[82:83] op_sel:[0,1,0]
	v_add_f32_dpp v110, v110, v110 row_ror:2 row_mask:0xf bank_mask:0xf bound_ctrl:1
	v_add_f32_dpp v111, v111, v111 row_ror:2 row_mask:0xf bank_mask:0xf bound_ctrl:1
	v_pk_fma_f32 v[116:117], v[4:5], v[10:11], v[116:117] op_sel_hi:[1,0,1]
	v_add_f32_dpp v110, v110, v110 row_ror:1 row_mask:0xf bank_mask:0xf bound_ctrl:1
	v_add_f32_dpp v111, v111, v111 row_ror:1 row_mask:0xf bank_mask:0xf bound_ctrl:1
	v_pk_fma_f32 v[114:115], v[6:7], v[10:11], v[114:115] op_sel:[0,1,0]
	v_pk_fma_f32 v[0:1], v[110:111], v[16:17], v[38:39] op_sel_hi:[1,0,1]
	v_pk_fma_f32 v[2:3], v[110:111], v[16:17], v[82:83] op_sel:[0,1,0]
	v_pk_fma_f32 v[4:5], v[110:111], v[18:19], v[116:117] op_sel_hi:[1,0,1]
	v_pk_fma_f32 v[6:7], v[110:111], v[18:19], v[114:115] op_sel:[0,1,0]
	v_pk_mul_f32 v[112:113], v[0:1], v[24:25] op_sel_hi:[1,0]
	v_pk_fma_f32 v[112:113], v[2:3], v[24:25], v[112:113] op_sel:[0,1,0]
	v_pk_fma_f32 v[112:113], v[4:5], v[26:27], v[112:113] op_sel_hi:[1,0,1]
	v_pk_fma_f32 v[112:113], v[6:7], v[26:27], v[112:113] op_sel:[0,1,0]
	ds_write_b32 v119, v112 offset:20480
	ds_write_b32 v119, v113 offset:20544
	s_waitcnt lgkmcnt(2)
	v_pk_mul_f32 v[110:111], v[0:1], v[34:35] op_sel_hi:[1,0]
	v_pk_mul_f32 v[38:39], v[108:109], v[78:79] op_sel_hi:[1,0]
	v_pk_fma_f32 v[110:111], v[2:3], v[34:35], v[110:111] op_sel:[0,1,0]
	v_pk_mul_f32 v[82:83], v[108:109], v[78:79] op_sel:[0,1]
	v_pk_fma_f32 v[110:111], v[4:5], v[36:37], v[110:111] op_sel_hi:[1,0,1]
	v_pk_mul_f32 v[116:117], v[108:109], v[80:81] op_sel_hi:[1,0]
	v_pk_fma_f32 v[110:111], v[6:7], v[36:37], v[110:111] op_sel:[0,1,0]
	v_pk_mul_f32 v[114:115], v[108:109], v[80:81] op_sel:[0,1]
	ds_read_b128 v[12:15], v69 offset:43264
	ds_read_b128 v[20:23], v69 offset:43776
	ds_read_b64 v[28:29], v118 offset:44288
	ds_read_b128 v[8:11], v69 offset:43008
	ds_read_b128 v[16:19], v69 offset:43520
	ds_read_b128 v[24:27], v69 offset:44032
	v_add_f32_dpp v110, v110, v110 row_ror:8 row_mask:0xf bank_mask:0xf bound_ctrl:1
	v_add_f32_dpp v111, v111, v111 row_ror:8 row_mask:0xf bank_mask:0xf bound_ctrl:1
	v_pk_fma_f32 v[38:39], v[0:1], v[30:31], v[38:39] op_sel_hi:[1,0,1]
	v_add_f32_dpp v110, v110, v110 row_ror:4 row_mask:0xf bank_mask:0xf bound_ctrl:1
	v_add_f32_dpp v111, v111, v111 row_ror:4 row_mask:0xf bank_mask:0xf bound_ctrl:1
	v_pk_fma_f32 v[82:83], v[2:3], v[30:31], v[82:83] op_sel:[0,1,0]
	v_add_f32_dpp v110, v110, v110 row_ror:2 row_mask:0xf bank_mask:0xf bound_ctrl:1
	v_add_f32_dpp v111, v111, v111 row_ror:2 row_mask:0xf bank_mask:0xf bound_ctrl:1
	v_pk_fma_f32 v[116:117], v[4:5], v[32:33], v[116:117] op_sel_hi:[1,0,1]
	v_add_f32_dpp v110, v110, v110 row_ror:1 row_mask:0xf bank_mask:0xf bound_ctrl:1
	v_add_f32_dpp v111, v111, v111 row_ror:1 row_mask:0xf bank_mask:0xf bound_ctrl:1
	v_pk_fma_f32 v[114:115], v[6:7], v[32:33], v[114:115] op_sel:[0,1,0]
	v_pk_fma_f32 v[0:1], v[110:111], v[74:75], v[38:39] op_sel_hi:[1,0,1]
	v_pk_fma_f32 v[2:3], v[110:111], v[74:75], v[82:83] op_sel:[0,1,0]
	v_pk_fma_f32 v[4:5], v[110:111], v[76:77], v[116:117] op_sel_hi:[1,0,1]
	v_pk_fma_f32 v[6:7], v[110:111], v[76:77], v[114:115] op_sel:[0,1,0]
	v_pk_mul_f32 v[112:113], v[0:1], v[104:105] op_sel_hi:[1,0]
	v_pk_fma_f32 v[112:113], v[2:3], v[104:105], v[112:113] op_sel:[0,1,0]
	v_pk_fma_f32 v[112:113], v[4:5], v[106:107], v[112:113] op_sel_hi:[1,0,1]
	v_pk_fma_f32 v[112:113], v[6:7], v[106:107], v[112:113] op_sel:[0,1,0]
	ds_write_b32 v119, v112 offset:22528
	ds_write_b32 v119, v113 offset:22592
	s_waitcnt lgkmcnt(2)
	v_pk_mul_f32 v[110:111], v[0:1], v[12:13] op_sel_hi:[1,0]
	v_pk_mul_f32 v[38:39], v[28:29], v[20:21] op_sel_hi:[1,0]
	v_pk_fma_f32 v[110:111], v[2:3], v[12:13], v[110:111] op_sel:[0,1,0]
	v_pk_mul_f32 v[82:83], v[28:29], v[20:21] op_sel:[0,1]
	v_pk_fma_f32 v[110:111], v[4:5], v[14:15], v[110:111] op_sel_hi:[1,0,1]
	v_pk_mul_f32 v[116:117], v[28:29], v[22:23] op_sel_hi:[1,0]
	v_pk_fma_f32 v[110:111], v[6:7], v[14:15], v[110:111] op_sel:[0,1,0]
	v_pk_mul_f32 v[114:115], v[28:29], v[22:23] op_sel:[0,1]
	ds_read_b128 v[34:37], v69 offset:44800
	ds_read_b128 v[78:81], v69 offset:45312
	ds_read_b64 v[108:109], v118 offset:45824
	ds_read_b128 v[30:33], v69 offset:44544
	ds_read_b128 v[74:77], v69 offset:45056
	ds_read_b128 v[104:107], v69 offset:45568
	v_add_f32_dpp v110, v110, v110 row_ror:8 row_mask:0xf bank_mask:0xf bound_ctrl:1
	v_add_f32_dpp v111, v111, v111 row_ror:8 row_mask:0xf bank_mask:0xf bound_ctrl:1
	v_pk_fma_f32 v[38:39], v[0:1], v[8:9], v[38:39] op_sel_hi:[1,0,1]
	v_add_f32_dpp v110, v110, v110 row_ror:4 row_mask:0xf bank_mask:0xf bound_ctrl:1
	v_add_f32_dpp v111, v111, v111 row_ror:4 row_mask:0xf bank_mask:0xf bound_ctrl:1
	v_pk_fma_f32 v[82:83], v[2:3], v[8:9], v[82:83] op_sel:[0,1,0]
	v_add_f32_dpp v110, v110, v110 row_ror:2 row_mask:0xf bank_mask:0xf bound_ctrl:1
	v_add_f32_dpp v111, v111, v111 row_ror:2 row_mask:0xf bank_mask:0xf bound_ctrl:1
	v_pk_fma_f32 v[116:117], v[4:5], v[10:11], v[116:117] op_sel_hi:[1,0,1]
	v_add_f32_dpp v110, v110, v110 row_ror:1 row_mask:0xf bank_mask:0xf bound_ctrl:1
	v_add_f32_dpp v111, v111, v111 row_ror:1 row_mask:0xf bank_mask:0xf bound_ctrl:1
	v_pk_fma_f32 v[114:115], v[6:7], v[10:11], v[114:115] op_sel:[0,1,0]
	v_pk_fma_f32 v[0:1], v[110:111], v[16:17], v[38:39] op_sel_hi:[1,0,1]
	v_pk_fma_f32 v[2:3], v[110:111], v[16:17], v[82:83] op_sel:[0,1,0]
	v_pk_fma_f32 v[4:5], v[110:111], v[18:19], v[116:117] op_sel_hi:[1,0,1]
	v_pk_fma_f32 v[6:7], v[110:111], v[18:19], v[114:115] op_sel:[0,1,0]
	v_pk_mul_f32 v[112:113], v[0:1], v[24:25] op_sel_hi:[1,0]
	v_pk_fma_f32 v[112:113], v[2:3], v[24:25], v[112:113] op_sel:[0,1,0]
	v_pk_fma_f32 v[112:113], v[4:5], v[26:27], v[112:113] op_sel_hi:[1,0,1]
	v_pk_fma_f32 v[112:113], v[6:7], v[26:27], v[112:113] op_sel:[0,1,0]
	ds_write_b32 v119, v112 offset:24576
	ds_write_b32 v119, v113 offset:24640
	s_waitcnt lgkmcnt(2)
	v_pk_mul_f32 v[110:111], v[0:1], v[34:35] op_sel_hi:[1,0]
	v_pk_mul_f32 v[38:39], v[108:109], v[78:79] op_sel_hi:[1,0]
	v_pk_fma_f32 v[110:111], v[2:3], v[34:35], v[110:111] op_sel:[0,1,0]
	v_pk_mul_f32 v[82:83], v[108:109], v[78:79] op_sel:[0,1]
	v_pk_fma_f32 v[110:111], v[4:5], v[36:37], v[110:111] op_sel_hi:[1,0,1]
	v_pk_mul_f32 v[116:117], v[108:109], v[80:81] op_sel_hi:[1,0]
	v_pk_fma_f32 v[110:111], v[6:7], v[36:37], v[110:111] op_sel:[0,1,0]
	v_pk_mul_f32 v[114:115], v[108:109], v[80:81] op_sel:[0,1]
	ds_read_b128 v[12:15], v69 offset:46336
	ds_read_b128 v[20:23], v69 offset:46848
	ds_read_b64 v[28:29], v118 offset:47360
	ds_read_b128 v[8:11], v69 offset:46080
	ds_read_b128 v[16:19], v69 offset:46592
	ds_read_b128 v[24:27], v69 offset:47104
	v_add_f32_dpp v110, v110, v110 row_ror:8 row_mask:0xf bank_mask:0xf bound_ctrl:1
	v_add_f32_dpp v111, v111, v111 row_ror:8 row_mask:0xf bank_mask:0xf bound_ctrl:1
	v_pk_fma_f32 v[38:39], v[0:1], v[30:31], v[38:39] op_sel_hi:[1,0,1]
	v_add_f32_dpp v110, v110, v110 row_ror:4 row_mask:0xf bank_mask:0xf bound_ctrl:1
	v_add_f32_dpp v111, v111, v111 row_ror:4 row_mask:0xf bank_mask:0xf bound_ctrl:1
	v_pk_fma_f32 v[82:83], v[2:3], v[30:31], v[82:83] op_sel:[0,1,0]
	v_add_f32_dpp v110, v110, v110 row_ror:2 row_mask:0xf bank_mask:0xf bound_ctrl:1
	v_add_f32_dpp v111, v111, v111 row_ror:2 row_mask:0xf bank_mask:0xf bound_ctrl:1
	v_pk_fma_f32 v[116:117], v[4:5], v[32:33], v[116:117] op_sel_hi:[1,0,1]
	v_add_f32_dpp v110, v110, v110 row_ror:1 row_mask:0xf bank_mask:0xf bound_ctrl:1
	v_add_f32_dpp v111, v111, v111 row_ror:1 row_mask:0xf bank_mask:0xf bound_ctrl:1
	v_pk_fma_f32 v[114:115], v[6:7], v[32:33], v[114:115] op_sel:[0,1,0]
	v_pk_fma_f32 v[0:1], v[110:111], v[74:75], v[38:39] op_sel_hi:[1,0,1]
	v_pk_fma_f32 v[2:3], v[110:111], v[74:75], v[82:83] op_sel:[0,1,0]
	v_pk_fma_f32 v[4:5], v[110:111], v[76:77], v[116:117] op_sel_hi:[1,0,1]
	v_pk_fma_f32 v[6:7], v[110:111], v[76:77], v[114:115] op_sel:[0,1,0]
	v_pk_mul_f32 v[112:113], v[0:1], v[104:105] op_sel_hi:[1,0]
	v_pk_fma_f32 v[112:113], v[2:3], v[104:105], v[112:113] op_sel:[0,1,0]
	v_pk_fma_f32 v[112:113], v[4:5], v[106:107], v[112:113] op_sel_hi:[1,0,1]
	v_pk_fma_f32 v[112:113], v[6:7], v[106:107], v[112:113] op_sel:[0,1,0]
	ds_write_b32 v119, v112 offset:26624
	ds_write_b32 v119, v113 offset:26688
	s_waitcnt lgkmcnt(2)
	v_pk_mul_f32 v[110:111], v[0:1], v[12:13] op_sel_hi:[1,0]
	v_pk_mul_f32 v[38:39], v[28:29], v[20:21] op_sel_hi:[1,0]
	v_pk_fma_f32 v[110:111], v[2:3], v[12:13], v[110:111] op_sel:[0,1,0]
	v_pk_mul_f32 v[82:83], v[28:29], v[20:21] op_sel:[0,1]
	v_pk_fma_f32 v[110:111], v[4:5], v[14:15], v[110:111] op_sel_hi:[1,0,1]
	v_pk_mul_f32 v[116:117], v[28:29], v[22:23] op_sel_hi:[1,0]
	v_pk_fma_f32 v[110:111], v[6:7], v[14:15], v[110:111] op_sel:[0,1,0]
	v_pk_mul_f32 v[114:115], v[28:29], v[22:23] op_sel:[0,1]
	ds_read_b128 v[34:37], v69 offset:47872
	ds_read_b128 v[78:81], v69 offset:48384
	ds_read_b64 v[108:109], v118 offset:48896
	ds_read_b128 v[30:33], v69 offset:47616
	ds_read_b128 v[74:77], v69 offset:48128
	ds_read_b128 v[104:107], v69 offset:48640
	v_add_f32_dpp v110, v110, v110 row_ror:8 row_mask:0xf bank_mask:0xf bound_ctrl:1
	v_add_f32_dpp v111, v111, v111 row_ror:8 row_mask:0xf bank_mask:0xf bound_ctrl:1
	v_pk_fma_f32 v[38:39], v[0:1], v[8:9], v[38:39] op_sel_hi:[1,0,1]
	v_add_f32_dpp v110, v110, v110 row_ror:4 row_mask:0xf bank_mask:0xf bound_ctrl:1
	v_add_f32_dpp v111, v111, v111 row_ror:4 row_mask:0xf bank_mask:0xf bound_ctrl:1
	v_pk_fma_f32 v[82:83], v[2:3], v[8:9], v[82:83] op_sel:[0,1,0]
	v_add_f32_dpp v110, v110, v110 row_ror:2 row_mask:0xf bank_mask:0xf bound_ctrl:1
	v_add_f32_dpp v111, v111, v111 row_ror:2 row_mask:0xf bank_mask:0xf bound_ctrl:1
	v_pk_fma_f32 v[116:117], v[4:5], v[10:11], v[116:117] op_sel_hi:[1,0,1]
	v_add_f32_dpp v110, v110, v110 row_ror:1 row_mask:0xf bank_mask:0xf bound_ctrl:1
	v_add_f32_dpp v111, v111, v111 row_ror:1 row_mask:0xf bank_mask:0xf bound_ctrl:1
	v_pk_fma_f32 v[114:115], v[6:7], v[10:11], v[114:115] op_sel:[0,1,0]
	v_pk_fma_f32 v[0:1], v[110:111], v[16:17], v[38:39] op_sel_hi:[1,0,1]
	v_pk_fma_f32 v[2:3], v[110:111], v[16:17], v[82:83] op_sel:[0,1,0]
	v_pk_fma_f32 v[4:5], v[110:111], v[18:19], v[116:117] op_sel_hi:[1,0,1]
	v_pk_fma_f32 v[6:7], v[110:111], v[18:19], v[114:115] op_sel:[0,1,0]
	v_pk_mul_f32 v[112:113], v[0:1], v[24:25] op_sel_hi:[1,0]
	v_pk_fma_f32 v[112:113], v[2:3], v[24:25], v[112:113] op_sel:[0,1,0]
	v_pk_fma_f32 v[112:113], v[4:5], v[26:27], v[112:113] op_sel_hi:[1,0,1]
	v_pk_fma_f32 v[112:113], v[6:7], v[26:27], v[112:113] op_sel:[0,1,0]
	ds_write_b32 v119, v112 offset:28672
	ds_write_b32 v119, v113 offset:28736
	s_waitcnt lgkmcnt(2)
	v_pk_mul_f32 v[110:111], v[0:1], v[34:35] op_sel_hi:[1,0]
	v_pk_mul_f32 v[38:39], v[108:109], v[78:79] op_sel_hi:[1,0]
	v_pk_fma_f32 v[110:111], v[2:3], v[34:35], v[110:111] op_sel:[0,1,0]
	v_pk_mul_f32 v[82:83], v[108:109], v[78:79] op_sel:[0,1]
	v_pk_fma_f32 v[110:111], v[4:5], v[36:37], v[110:111] op_sel_hi:[1,0,1]
	v_pk_mul_f32 v[116:117], v[108:109], v[80:81] op_sel_hi:[1,0]
	v_pk_fma_f32 v[110:111], v[6:7], v[36:37], v[110:111] op_sel:[0,1,0]
	v_pk_mul_f32 v[114:115], v[108:109], v[80:81] op_sel:[0,1]
	s_nop 0
	v_add_f32_dpp v110, v110, v110 row_ror:8 row_mask:0xf bank_mask:0xf bound_ctrl:1
	v_add_f32_dpp v111, v111, v111 row_ror:8 row_mask:0xf bank_mask:0xf bound_ctrl:1
	v_pk_fma_f32 v[38:39], v[0:1], v[30:31], v[38:39] op_sel_hi:[1,0,1]
	v_add_f32_dpp v110, v110, v110 row_ror:4 row_mask:0xf bank_mask:0xf bound_ctrl:1
	v_add_f32_dpp v111, v111, v111 row_ror:4 row_mask:0xf bank_mask:0xf bound_ctrl:1
	v_pk_fma_f32 v[82:83], v[2:3], v[30:31], v[82:83] op_sel:[0,1,0]
	v_add_f32_dpp v110, v110, v110 row_ror:2 row_mask:0xf bank_mask:0xf bound_ctrl:1
	v_add_f32_dpp v111, v111, v111 row_ror:2 row_mask:0xf bank_mask:0xf bound_ctrl:1
	v_pk_fma_f32 v[116:117], v[4:5], v[32:33], v[116:117] op_sel_hi:[1,0,1]
	v_add_f32_dpp v110, v110, v110 row_ror:1 row_mask:0xf bank_mask:0xf bound_ctrl:1
	v_add_f32_dpp v111, v111, v111 row_ror:1 row_mask:0xf bank_mask:0xf bound_ctrl:1
	v_pk_fma_f32 v[114:115], v[6:7], v[32:33], v[114:115] op_sel:[0,1,0]
	v_pk_fma_f32 v[0:1], v[110:111], v[74:75], v[38:39] op_sel_hi:[1,0,1]
	v_pk_fma_f32 v[2:3], v[110:111], v[74:75], v[82:83] op_sel:[0,1,0]
	v_pk_fma_f32 v[4:5], v[110:111], v[76:77], v[116:117] op_sel_hi:[1,0,1]
	v_pk_fma_f32 v[6:7], v[110:111], v[76:77], v[114:115] op_sel:[0,1,0]
	v_pk_mul_f32 v[112:113], v[0:1], v[104:105] op_sel_hi:[1,0]
	v_pk_fma_f32 v[112:113], v[2:3], v[104:105], v[112:113] op_sel:[0,1,0]
	v_pk_fma_f32 v[112:113], v[4:5], v[106:107], v[112:113] op_sel_hi:[1,0,1]
	v_pk_fma_f32 v[112:113], v[6:7], v[106:107], v[112:113] op_sel:[0,1,0]
	ds_write_b32 v119, v112 offset:30720
	ds_write_b32 v119, v113 offset:30784
	s_setprio 0
	s_branch .LBB0_140
